# P4 latency chains: b_forget scalars preloaded (16 dependent loads -> 1), scan waves skip the row loop, row loop preloads all its rows
# speedup vs baseline: 1.0295x; 1.0059x over previous
; #define IN_b_forget PTRF(5)
; __global__ void __launch_bounds__(512, 2) fwd_kernel(Args a) {
;     ...
;     if (IN(4)) for (int rep = 0; rep < REPS(4); ++rep) { DECL_WS();
;         if (gw < 128) {
;             const int b = gw >> 6, ch = gw & 63; const float* const bfp = IN_b_forget; float* const totp = (float*)(ws + WS_TOT);
;             const bf16_t* fp = proj + (size_t)(b * SEQ + ch * 64 + lane) * NPROJ + PC_F;
;             const u32x4 f0 = *(const u32x4*)fp, f1 = *(const u32x4*)(fp + 8);
;             float fz[16] = {bflo(f0.x), bfhi(f0.x), bflo(f0.y), bfhi(f0.y), bflo(f0.z), bfhi(f0.z), bflo(f0.w), bfhi(f0.w),
;                             bflo(f1.x), bfhi(f1.x), bflo(f1.y), bfhi(f1.y), bflo(f1.z), bfhi(f1.z), bflo(f1.w), bfhi(f1.w)};
; #pragma unroll
;             for (int hh = 0; hh < 16; ++hh) { const float z = fz[hh] + bfp[hh]; float incl = (fminf(z, 0.f) - log1pf(__expf(-fabsf(z)))) * LOG2E;
; #pragma unroll
;                 for (int o = 1; o < 64; o <<= 1) { const float t = __shfl_up(incl, o); if (lane >= o) incl += t; }
;                 cum[(size_t)(b * 16 + hh) * SEQ + ch * 64 + lane] = incl; ((float*)(ws + WS_NCUM))[(size_t)(b * 16 + hh) * SEQ + ch * 64 + lane] = -incl;
;                 if (lane == 63) totp[(b * 16 + hh) * 64 + ch] = incl; }
.LBB0_451:
	s_cmp_lt_i32 s90, 5
	s_cselect_b64 s[0:1], -1, 0
	s_and_b64 s[16:17], s[0:1], s[2:3]
	s_andn2_b64 vcc, exec, s[16:17]
	v_cmp_eq_u32_e64 s[2:3], 0, v196
	v_cmp_gt_u32_e64 s[4:5], 32, v196
	v_cmp_gt_u32_e64 s[6:7], 8, v196
	s_cbranch_vccnz .LBB0_497
	s_add_i32 s0, 0, 0x220a0
	v_mov_b32_e32 v2, s0
	ds_read_b64 v[2:3], v2
	s_cmpk_gt_i32 s96, 0x7f
	s_waitcnt lgkmcnt(0)
	v_readfirstlane_b32 s18, v2
	v_readfirstlane_b32 s19, v3
	s_cbranch_scc1 .LBB0_486
	s_ashr_i32 s33, s96, 6
	s_and_b32 s15, s96, 63
	s_lshl_b32 s12, s15, 6
	s_lshl_b32 s22, s33, 4
	s_add_u32 s20, s18, 0x400000
	s_addc_u32 s21, s19, 0
	s_add_i32 s1, 0, 0x22028
	v_mov_b32_e32 v2, s1
	s_lshl_b32 s0, s33, 12
	ds_read_b64 v[2:3], v2
	s_or_b32 s0, s0, s12
	v_or_b32_e32 v4, s0, v196
	v_ashrrev_i32_e32 v5, 31, v4
	v_lshlrev_b64 v[4:5], 14, v[4:5]
	s_waitcnt lgkmcnt(0)
	v_readfirstlane_b32 s24, v2
	v_readfirstlane_b32 s25, v3
	v_lshl_add_u64 v[2:3], s[18:19], 0, v[4:5]
	s_mov_b32 s0, 0x7c01000
	v_add_co_u32_e32 v4, vcc, s0, v2
	v_mov_b32_e32 v21, 0
	s_nop 0
	v_addc_co_u32_e32 v5, vcc, 0, v3, vcc
	global_load_dwordx4 v[6:9], v[4:5], off offset:3584
	global_load_dword v10, v21, s[24:25]
	global_load_dword v41, v21, s[24:25] offset:4
	global_load_dword v42, v21, s[24:25] offset:8
	global_load_dword v43, v21, s[24:25] offset:12
	global_load_dword v44, v21, s[24:25] offset:16
	global_load_dword v45, v21, s[24:25] offset:20
	global_load_dword v46, v21, s[24:25] offset:24
	global_load_dword v47, v21, s[24:25] offset:28
	global_load_dword v48, v21, s[24:25] offset:32
	global_load_dword v49, v21, s[24:25] offset:36
	global_load_dword v50, v21, s[24:25] offset:40
	global_load_dword v51, v21, s[24:25] offset:44
	global_load_dword v52, v21, s[24:25] offset:48
	global_load_dword v53, v21, s[24:25] offset:52
	global_load_dword v54, v21, s[24:25] offset:56
	global_load_dword v55, v21, s[24:25] offset:60
	s_mov_b32 s36, 0xbfb8aa3b
	s_mov_b32 s35, 0x3f2aaaab
	s_mov_b32 s34, 0x3f317218
	s_mov_b64 s[0:1], 0x7c01e00
	v_mbcnt_lo_u32_b32 v4, -1, 0
	v_lshl_add_u64 v[2:3], v[2:3], 0, s[0:1]
	v_mov_b32_e32 v17, 0x3ecc95a3
	v_mbcnt_hi_u32_b32 v16, -1, v4
	global_load_dwordx4 v[2:5], v[2:3], off offset:16
	s_mov_b32 s28, 0x7f800000
	v_mov_b32_e32 v18, 0x7f800000
	v_mov_b32_e32 v19, 0x7fc00000
	v_mov_b32_e32 v20, 0xff800000
	s_mov_b32 s29, 0x33800000
	v_and_b32_e32 v22, 64, v16
	v_add_u32_e32 v13, -1, v16
	v_cmp_gt_u32_e64 s[8:9], 2, v196
	v_cmp_gt_u32_e64 s[10:11], 4, v196
	s_add_u32 s30, s18, 0x200000
	s_addc_u32 s31, s19, 0
	s_add_u32 s26, s18, 0x300000
	s_addc_u32 s27, s19, 0
	s_ashr_i32 s23, s22, 31
	s_waitcnt vmcnt(0)
	v_lshlrev_b32_e32 v11, 16, v6
	v_add_f32_e32 v10, v10, v11
	v_mul_f32_e64 v11, |v10|, s36
	v_exp_f32_e32 v12, v11
	v_min_f32_e32 v14, 0, v10
	v_add_f32_e32 v15, 1.0, v12
	v_add_f32_e32 v23, -1.0, v15
	v_frexp_mant_f32_e32 v24, v15
	v_cvt_f64_f32_e32 v[10:11], v15
	v_sub_f32_e32 v25, v23, v15
	v_frexp_exp_i32_f64_e32 v10, v[10:11]
	v_cmp_gt_f32_e32 vcc, s35, v24
	v_sub_f32_e32 v23, v12, v23
	v_add_f32_e32 v11, 1.0, v25
	v_subbrev_co_u32_e32 v10, vcc, 0, v10, vcc
	v_add_f32_e32 v11, v23, v11
	v_sub_u32_e32 v23, 0, v10
	v_cvt_f32_i32_e32 v10, v10
	v_ldexp_f32 v15, v15, v23
	v_ldexp_f32 v11, v11, v23
	v_add_f32_e32 v23, -1.0, v15
	v_add_f32_e32 v24, 1.0, v15
	v_add_f32_e32 v25, 1.0, v23
	v_add_f32_e32 v26, -1.0, v24
	v_sub_f32_e32 v25, v15, v25
	v_sub_f32_e32 v15, v15, v26
	v_mul_f32_e32 v26, 0x3f317218, v10
	v_add_f32_e32 v25, v11, v25
	v_add_f32_e32 v11, v11, v15
	v_fma_f32 v15, v10, s34, -v26
	v_add_f32_e32 v27, v23, v25
	v_add_f32_e32 v28, v24, v11
	v_fmac_f32_e32 v15, 0xb102e308, v10
	v_sub_f32_e32 v10, v27, v23
	v_sub_f32_e32 v23, v28, v24
	v_rcp_f32_e32 v24, v28
	v_add_f32_e32 v29, v26, v15
	v_sub_f32_e32 v11, v11, v23
	v_sub_f32_e32 v23, v29, v26
	v_sub_f32_e32 v15, v15, v23
	v_mul_f32_e32 v23, v27, v24
	v_sub_f32_e32 v10, v25, v10
	v_mul_f32_e32 v25, v28, v23
	v_fma_f32 v26, v23, v28, -v25
	v_fmac_f32_e32 v26, v23, v11
	v_add_f32_e32 v30, v25, v26
	v_sub_f32_e32 v31, v27, v30
	v_sub_f32_e32 v25, v30, v25
	v_sub_f32_e32 v27, v27, v31
	v_sub_f32_e32 v25, v25, v26
	v_sub_f32_e32 v26, v27, v30
	v_add_f32_e32 v10, v10, v26
	v_add_f32_e32 v10, v25, v10
	v_add_f32_e32 v25, v31, v10
	v_mul_f32_e32 v26, v24, v25
	v_sub_f32_e32 v27, v31, v25
	v_mul_f32_e32 v30, v28, v26
	v_add_f32_e32 v10, v10, v27
	v_add_f32_e32 v27, v23, v26
	v_fma_f32 v28, v26, v28, -v30
	v_sub_f32_e32 v23, v27, v23
	v_fmac_f32_e32 v28, v26, v11
	v_sub_f32_e32 v11, v26, v23
	v_add_f32_e32 v23, v30, v28
	v_sub_f32_e32 v26, v23, v30
	v_sub_f32_e32 v30, v25, v23
	v_sub_f32_e32 v25, v25, v30
	v_sub_f32_e32 v23, v25, v23
	v_sub_f32_e32 v26, v26, v28
	v_add_f32_e32 v10, v10, v23
	v_add_f32_e32 v10, v26, v10
	v_add_f32_e32 v10, v30, v10
	v_mul_f32_e32 v10, v24, v10
	v_add_f32_e32 v10, v11, v10
	v_add_f32_e32 v11, v27, v10
	v_mul_f32_e32 v23, v11, v11
	v_fmamk_f32 v26, v23, 0x3e9b6dac, v17
	v_sub_f32_e32 v24, v11, v27
	v_ldexp_f32 v25, v11, 1
	v_mul_f32_e32 v11, v11, v23
	v_fmaak_f32 v23, v23, v26, 0x3f2aaada
	v_mul_f32_e32 v11, v11, v23
	v_add_f32_e32 v23, v25, v11
	v_sub_f32_e32 v10, v10, v24
	v_sub_f32_e32 v24, v23, v25
	v_ldexp_f32 v10, v10, 1
	v_sub_f32_e32 v11, v11, v24
	v_add_f32_e32 v10, v10, v11
	v_add_f32_e32 v11, v23, v10
	v_sub_f32_e32 v23, v11, v23
	v_add_f32_e32 v24, v29, v11
	v_sub_f32_e32 v10, v10, v23
	v_sub_f32_e32 v23, v24, v29
	v_sub_f32_e32 v25, v24, v23
	v_sub_f32_e32 v11, v11, v23
	v_add_f32_e32 v23, v15, v10
	v_sub_f32_e32 v25, v29, v25
	v_sub_f32_e32 v26, v23, v15
	v_add_f32_e32 v11, v11, v25
	v_sub_f32_e32 v25, v23, v26
	v_sub_f32_e32 v10, v10, v26
	v_sub_f32_e32 v15, v15, v25
	v_add_f32_e32 v11, v23, v11
	v_add_f32_e32 v10, v10, v15
	v_add_f32_e32 v15, v24, v11
	v_sub_f32_e32 v23, v15, v24
	v_sub_f32_e32 v11, v11, v23
	v_add_f32_e32 v10, v10, v11
	v_add_f32_e32 v10, v15, v10
	v_cmp_neq_f32_e32 vcc, s28, v12
	s_nop 1
	v_cndmask_b32_e32 v10, v18, v10, vcc
	v_cmp_ngt_f32_e32 vcc, -1.0, v12
	s_nop 1
	v_cndmask_b32_e32 v10, v19, v10, vcc
	v_cmp_neq_f32_e32 vcc, -1.0, v12
	s_nop 1
	v_cndmask_b32_e32 v10, v20, v10, vcc
	v_cmp_lt_f32_e64 vcc, |v12|, s29
	s_nop 1
	v_cndmask_b32_e32 v10, v10, v12, vcc
	v_cmp_lt_i32_e32 vcc, v13, v22
	v_sub_f32_e32 v11, v14, v10
	v_mul_f32_e32 v12, 0x3fb8aa3b, v11
	v_cndmask_b32_e32 v10, v13, v16, vcc
	v_lshlrev_b32_e32 v10, 2, v10
	ds_bpermute_b32 v13, v10, v12
	v_add_u32_e32 v14, -2, v16
	v_cmp_lt_i32_e32 vcc, v14, v22
	s_waitcnt lgkmcnt(0)
; __global__ void __launch_bounds__(512, 2) fwd_kernel(Args a) {
;     ...
;             for (int hh = 0; hh < 16; ++hh) { const float z = fz[hh] + bfp[hh]; float incl = (fminf(z, 0.f) - log1pf(__expf(-fabsf(z)))) * LOG2E;
; #pragma unroll
;                 for (int o = 1; o < 64; o <<= 1) { const float t = __shfl_up(incl, o); if (lane >= o) incl += t; }
;                 cum[(size_t)(b * 16 + hh) * SEQ + ch * 64 + lane] = incl; ((float*)(ws + WS_NCUM))[(size_t)(b * 16 + hh) * SEQ + ch * 64 + lane] = -incl;
;                 if (lane == 63) totp[(b * 16 + hh) * 64 + ch] = incl; }
	v_fmac_f32_e32 v13, 0x3fb8aa3b, v11
	v_cndmask_b32_e32 v11, v14, v16, vcc
	v_cndmask_b32_e64 v12, v13, v12, s[2:3]
	v_lshlrev_b32_e32 v11, 2, v11
	ds_bpermute_b32 v13, v11, v12
	v_add_u32_e32 v14, -4, v16
	v_cmp_lt_i32_e32 vcc, v14, v22
	s_waitcnt lgkmcnt(0)
	v_add_f32_e32 v13, v12, v13
	v_cndmask_b32_e64 v12, v13, v12, s[8:9]
	v_cndmask_b32_e32 v13, v14, v16, vcc
	v_lshlrev_b32_e32 v13, 2, v13
	ds_bpermute_b32 v14, v13, v12
	s_waitcnt lgkmcnt(0)
	v_add_f32_e32 v14, v12, v14
	v_cndmask_b32_e64 v12, v14, v12, s[10:11]
	v_add_u32_e32 v14, -8, v16
	v_cmp_lt_i32_e32 vcc, v14, v22
	s_nop 1
	v_cndmask_b32_e32 v14, v14, v16, vcc
	v_lshlrev_b32_e32 v14, 2, v14
	ds_bpermute_b32 v15, v14, v12
	s_waitcnt lgkmcnt(0)
	v_add_f32_e32 v15, v12, v15
	v_cndmask_b32_e64 v23, v15, v12, s[6:7]
	v_add_u32_e32 v12, -16, v16
	v_cmp_lt_i32_e32 vcc, v12, v22
	s_nop 1
	v_cndmask_b32_e32 v12, v12, v16, vcc
	v_lshlrev_b32_e32 v15, 2, v12
	ds_bpermute_b32 v24, v15, v23
	v_or_b32_e32 v12, s12, v196
	v_cmp_gt_u32_e64 s[12:13], 16, v196
	v_cmp_eq_u32_e32 vcc, 63, v196
	s_waitcnt lgkmcnt(0)
	v_add_f32_e32 v24, v23, v24
	v_cndmask_b32_e64 v24, v24, v23, s[12:13]
	v_subrev_u32_e32 v23, 32, v16
	v_cmp_lt_i32_e64 s[0:1], v23, v22
	v_mov_b32_e32 v22, 0x3f2aaada
	s_nop 0
	v_cndmask_b32_e64 v16, v23, v16, s[0:1]
	v_lshlrev_b32_e32 v16, 2, v16
	ds_bpermute_b32 v23, v16, v24
	s_lshl_b64 s[0:1], s[22:23], 14
	v_mov_b32_e32 v25, s1
	s_waitcnt lgkmcnt(0)
	v_add_f32_e32 v23, v24, v23
	v_cndmask_b32_e64 v28, v23, v24, s[4:5]
	v_lshl_or_b32 v24, v12, 2, s0
	v_lshl_add_u64 v[26:27], s[20:21], 0, v[24:25]
	global_store_dword v[26:27], v28, off
	v_xor_b32_e32 v26, 0x80000000, v28
	v_lshl_add_u64 v[24:25], s[26:27], 0, v[24:25]
	global_store_dword v[24:25], v26, off
	s_and_saveexec_b64 s[0:1], vcc
	s_cbranch_execz .LBB0_455
	s_lshl_b32 s23, s33, 10
	s_or_b32 s38, s23, s15
	s_ashr_i32 s39, s38, 31
	s_lshl_b64 s[38:39], s[38:39], 2
	s_add_u32 s38, s30, s38
	s_addc_u32 s39, s31, s39
	global_store_dword v21, v23, s[38:39]
.LBB0_455:
	s_or_b64 exec, exec, s[0:1]
	v_mov_b32_e32 v21, v41
	v_and_b32_e32 v6, 0xffff0000, v6
	v_add_f32_e32 v6, v21, v6
	v_mul_f32_e64 v21, |v6|, s36
	v_exp_f32_e32 v21, v21
	v_min_f32_e32 v6, 0, v6
	v_add_f32_e32 v23, 1.0, v21
	v_add_f32_e32 v26, -1.0, v23
	v_frexp_mant_f32_e32 v27, v23
	v_cvt_f64_f32_e32 v[24:25], v23
	v_sub_f32_e32 v28, v26, v23
	v_frexp_exp_i32_f64_e32 v24, v[24:25]
	v_cmp_gt_f32_e64 s[0:1], s35, v27
	v_sub_f32_e32 v26, v21, v26
	v_add_f32_e32 v25, 1.0, v28
	v_subbrev_co_u32_e64 v24, s[0:1], 0, v24, s[0:1]
	v_add_f32_e32 v25, v26, v25
	v_sub_u32_e32 v26, 0, v24
	v_cvt_f32_i32_e32 v24, v24
	v_ldexp_f32 v23, v23, v26
	v_ldexp_f32 v25, v25, v26
	v_add_f32_e32 v26, -1.0, v23
	v_add_f32_e32 v27, 1.0, v23
	v_add_f32_e32 v28, 1.0, v26
	v_add_f32_e32 v29, -1.0, v27
	v_sub_f32_e32 v28, v23, v28
	v_sub_f32_e32 v23, v23, v29
	v_mul_f32_e32 v29, 0x3f317218, v24
	v_add_f32_e32 v28, v25, v28
	v_add_f32_e32 v23, v25, v23
	v_fma_f32 v25, v24, s34, -v29
	v_add_f32_e32 v30, v26, v28
	v_add_f32_e32 v31, v27, v23
	v_fmac_f32_e32 v25, 0xb102e308, v24
	v_sub_f32_e32 v24, v30, v26
	v_sub_f32_e32 v26, v31, v27
	v_rcp_f32_e32 v27, v31
	v_add_f32_e32 v32, v29, v25
	v_sub_f32_e32 v23, v23, v26
	v_sub_f32_e32 v26, v32, v29
	v_sub_f32_e32 v25, v25, v26
	v_mul_f32_e32 v26, v30, v27
	v_sub_f32_e32 v24, v28, v24
	v_mul_f32_e32 v28, v31, v26
	v_fma_f32 v29, v26, v31, -v28
	v_fmac_f32_e32 v29, v26, v23
	v_add_f32_e32 v33, v28, v29
	v_sub_f32_e32 v34, v30, v33
	v_sub_f32_e32 v28, v33, v28
	v_sub_f32_e32 v30, v30, v34
	v_sub_f32_e32 v28, v28, v29
	v_sub_f32_e32 v29, v30, v33
	v_add_f32_e32 v24, v24, v29
	v_add_f32_e32 v24, v28, v24
	v_add_f32_e32 v28, v34, v24
	v_mul_f32_e32 v29, v27, v28
	v_sub_f32_e32 v30, v34, v28
	v_mul_f32_e32 v33, v31, v29
	v_add_f32_e32 v24, v24, v30
	v_add_f32_e32 v30, v26, v29
	v_fma_f32 v31, v29, v31, -v33
	v_sub_f32_e32 v26, v30, v26
	v_fmac_f32_e32 v31, v29, v23
	v_sub_f32_e32 v23, v29, v26
	v_add_f32_e32 v26, v33, v31
	v_sub_f32_e32 v29, v26, v33
	v_sub_f32_e32 v33, v28, v26
	v_sub_f32_e32 v28, v28, v33
	v_sub_f32_e32 v26, v28, v26
	v_sub_f32_e32 v29, v29, v31
	v_add_f32_e32 v24, v24, v26
	v_add_f32_e32 v24, v29, v24
	v_add_f32_e32 v24, v33, v24
	v_mul_f32_e32 v24, v27, v24
	v_add_f32_e32 v23, v23, v24
	v_add_f32_e32 v24, v30, v23
	v_mul_f32_e32 v26, v24, v24
	v_fmac_f32_e32 v17, 0x3e9b6dac, v26
	v_sub_f32_e32 v27, v24, v30
	v_ldexp_f32 v28, v24, 1
	v_mul_f32_e32 v24, v24, v26
	v_fmac_f32_e32 v22, v26, v17
	v_sub_f32_e32 v23, v23, v27
	v_mul_f32_e32 v22, v24, v22
	v_ldexp_f32 v17, v23, 1
	v_add_f32_e32 v23, v28, v22
	v_sub_f32_e32 v24, v23, v28
	v_sub_f32_e32 v22, v22, v24
	v_add_f32_e32 v17, v17, v22
	v_add_f32_e32 v22, v23, v17
	v_sub_f32_e32 v23, v22, v23
	v_add_f32_e32 v24, v32, v22
	v_sub_f32_e32 v17, v17, v23
	v_sub_f32_e32 v23, v24, v32
	v_sub_f32_e32 v26, v24, v23
	v_sub_f32_e32 v22, v22, v23
	v_sub_f32_e32 v26, v32, v26
	v_add_f32_e32 v23, v25, v17
	v_add_f32_e32 v22, v22, v26
	v_sub_f32_e32 v27, v23, v25
	v_add_f32_e32 v22, v23, v22
	v_sub_f32_e32 v26, v23, v27
	v_add_f32_e32 v23, v24, v22
	v_sub_f32_e32 v17, v17, v27
	v_sub_f32_e32 v25, v25, v26
	v_sub_f32_e32 v24, v23, v24
	v_add_f32_e32 v17, v17, v25
	v_sub_f32_e32 v22, v22, v24
	v_add_f32_e32 v17, v17, v22
	v_add_f32_e32 v17, v23, v17
	v_cmp_neq_f32_e64 s[0:1], s28, v21
	s_nop 1
	v_cndmask_b32_e64 v17, v18, v17, s[0:1]
	v_cmp_ngt_f32_e64 s[0:1], -1.0, v21
	s_nop 1
	v_cndmask_b32_e64 v17, v19, v17, s[0:1]
	v_cmp_neq_f32_e64 s[0:1], -1.0, v21
	s_nop 1
	v_cndmask_b32_e64 v17, v20, v17, s[0:1]
	v_cmp_lt_f32_e64 s[0:1], |v21|, s29
	s_nop 1
	v_cndmask_b32_e64 v17, v17, v21, s[0:1]
	v_sub_f32_e32 v6, v6, v17
	v_mul_f32_e32 v17, 0x3fb8aa3b, v6
	ds_bpermute_b32 v18, v10, v17
	s_or_b32 s0, s22, 1
	s_ashr_i32 s1, s0, 31
	s_lshl_b64 s[28:29], s[0:1], 14
	v_mov_b32_e32 v19, s29
	s_waitcnt lgkmcnt(0)
	v_fmac_f32_e32 v18, 0x3fb8aa3b, v6
	v_cndmask_b32_e64 v6, v18, v17, s[2:3]
	ds_bpermute_b32 v17, v11, v6
	v_lshl_or_b32 v18, v12, 2, s28
	v_lshl_add_u64 v[20:21], s[20:21], 0, v[18:19]
	v_lshl_add_u64 v[18:19], s[26:27], 0, v[18:19]
	s_waitcnt lgkmcnt(0)
	v_add_f32_e32 v17, v6, v17
	v_cndmask_b32_e64 v6, v17, v6, s[8:9]
	ds_bpermute_b32 v17, v13, v6
	s_waitcnt lgkmcnt(0)
	v_add_f32_e32 v17, v6, v17
	v_cndmask_b32_e64 v6, v17, v6, s[10:11]
	ds_bpermute_b32 v17, v14, v6
	s_waitcnt lgkmcnt(0)
	v_add_f32_e32 v17, v6, v17
	v_cndmask_b32_e64 v6, v17, v6, s[6:7]
	ds_bpermute_b32 v17, v15, v6
	s_waitcnt lgkmcnt(0)
	v_add_f32_e32 v17, v6, v17
	v_cndmask_b32_e64 v17, v17, v6, s[12:13]
	ds_bpermute_b32 v6, v16, v17
	s_waitcnt lgkmcnt(0)
	v_add_f32_e32 v6, v17, v6
	v_cndmask_b32_e64 v17, v6, v17, s[4:5]
	global_store_dword v[20:21], v17, off
	v_xor_b32_e32 v17, 0x80000000, v17
	global_store_dword v[18:19], v17, off
	s_and_saveexec_b64 s[28:29], vcc
	s_cbranch_execz .LBB0_457
	s_lshl_b32 s0, s0, 6
	s_or_b32 s0, s0, s15
	s_ashr_i32 s1, s0, 31
	s_lshl_b64 s[0:1], s[0:1], 2
	s_add_u32 s0, s30, s0
	s_addc_u32 s1, s31, s1
	v_mov_b32_e32 v17, 0
	global_store_dword v17, v6, s[0:1]
; __global__ void __launch_bounds__(512, 2) fwd_kernel(Args a) {
;     ...
;             for (int hh = 0; hh < 16; ++hh) { const float z = fz[hh] + bfp[hh]; float incl = (fminf(z, 0.f) - log1pf(__expf(-fabsf(z)))) * LOG2E;
; #pragma unroll
;                 for (int o = 1; o < 64; o <<= 1) { const float t = __shfl_up(incl, o); if (lane >= o) incl += t; }
;                 cum[(size_t)(b * 16 + hh) * SEQ + ch * 64 + lane] = incl; ((float*)(ws + WS_NCUM))[(size_t)(b * 16 + hh) * SEQ + ch * 64 + lane] = -incl;
;                 if (lane == 63) totp[(b * 16 + hh) * 64 + ch] = incl; }
.LBB0_457:
	s_or_b64 exec, exec, s[28:29]
	v_mov_b32_e32 v20, 0
	v_mov_b32_e32 v19, v42
	v_lshlrev_b32_e32 v21, 16, v7
	v_mov_b32_e32 v6, 0x3ecc95a3
	s_mov_b32 s23, 0x7f800000
	v_mov_b32_e32 v17, 0x7f800000
	v_mov_b32_e32 v18, 0x7fc00000
	s_mov_b32 s33, 0x33800000
	v_add_f32_e32 v21, v19, v21
	v_mul_f32_e64 v19, |v21|, s36
	v_exp_f32_e32 v24, v19
	v_mov_b32_e32 v19, 0xff800000
	v_min_f32_e32 v21, 0, v21
	v_add_f32_e32 v25, 1.0, v24
	v_add_f32_e32 v26, -1.0, v25
	v_frexp_mant_f32_e32 v27, v25
	v_cvt_f64_f32_e32 v[22:23], v25
	v_sub_f32_e32 v28, v26, v25
	v_frexp_exp_i32_f64_e32 v22, v[22:23]
	v_cmp_gt_f32_e64 s[0:1], s35, v27
	v_sub_f32_e32 v26, v24, v26
	v_add_f32_e32 v23, 1.0, v28
	v_subbrev_co_u32_e64 v22, s[0:1], 0, v22, s[0:1]
	v_add_f32_e32 v23, v26, v23
	v_sub_u32_e32 v26, 0, v22
	v_cvt_f32_i32_e32 v22, v22
	v_ldexp_f32 v25, v25, v26
	v_ldexp_f32 v23, v23, v26
	v_add_f32_e32 v26, -1.0, v25
	v_add_f32_e32 v27, 1.0, v25
	v_add_f32_e32 v28, 1.0, v26
	v_add_f32_e32 v29, -1.0, v27
	v_sub_f32_e32 v28, v25, v28
	v_sub_f32_e32 v25, v25, v29
	v_mul_f32_e32 v29, 0x3f317218, v22
	v_add_f32_e32 v28, v23, v28
	v_add_f32_e32 v23, v23, v25
	v_fma_f32 v25, v22, s34, -v29
	v_add_f32_e32 v30, v26, v28
	v_add_f32_e32 v31, v27, v23
	v_fmac_f32_e32 v25, 0xb102e308, v22
	v_sub_f32_e32 v22, v30, v26
	v_sub_f32_e32 v26, v31, v27
	v_rcp_f32_e32 v27, v31
	v_add_f32_e32 v32, v29, v25
	v_sub_f32_e32 v23, v23, v26
	v_sub_f32_e32 v26, v32, v29
	v_sub_f32_e32 v25, v25, v26
	v_mul_f32_e32 v26, v30, v27
	v_sub_f32_e32 v22, v28, v22
	v_mul_f32_e32 v28, v31, v26
	v_fma_f32 v29, v26, v31, -v28
	v_fmac_f32_e32 v29, v26, v23
	v_add_f32_e32 v33, v28, v29
	v_sub_f32_e32 v34, v30, v33
	v_sub_f32_e32 v28, v33, v28
	v_sub_f32_e32 v30, v30, v34
	v_sub_f32_e32 v28, v28, v29
	v_sub_f32_e32 v29, v30, v33
	v_add_f32_e32 v22, v22, v29
	v_add_f32_e32 v22, v28, v22
	v_add_f32_e32 v28, v34, v22
	v_mul_f32_e32 v29, v27, v28
	v_sub_f32_e32 v30, v34, v28
	v_mul_f32_e32 v33, v31, v29
	v_add_f32_e32 v22, v22, v30
	v_add_f32_e32 v30, v26, v29
	v_fma_f32 v31, v29, v31, -v33
	v_sub_f32_e32 v26, v30, v26
	v_fmac_f32_e32 v31, v29, v23
	v_sub_f32_e32 v23, v29, v26
	v_add_f32_e32 v26, v33, v31
	v_sub_f32_e32 v29, v26, v33
	v_sub_f32_e32 v33, v28, v26
	v_sub_f32_e32 v28, v28, v33
	v_sub_f32_e32 v26, v28, v26
	v_sub_f32_e32 v29, v29, v31
	v_add_f32_e32 v22, v22, v26
	v_add_f32_e32 v22, v29, v22
	v_add_f32_e32 v22, v33, v22
	v_mul_f32_e32 v22, v27, v22
	v_add_f32_e32 v22, v23, v22
	v_add_f32_e32 v23, v30, v22
	v_mul_f32_e32 v26, v23, v23
	v_fmamk_f32 v29, v26, 0x3e9b6dac, v6
	v_sub_f32_e32 v27, v23, v30
	v_ldexp_f32 v28, v23, 1
	v_mul_f32_e32 v23, v23, v26
	v_fmaak_f32 v26, v26, v29, 0x3f2aaada
	v_mul_f32_e32 v23, v23, v26
	v_add_f32_e32 v26, v28, v23
	v_sub_f32_e32 v22, v22, v27
	v_sub_f32_e32 v27, v26, v28
	v_ldexp_f32 v22, v22, 1
	v_sub_f32_e32 v23, v23, v27
	v_add_f32_e32 v22, v22, v23
	v_add_f32_e32 v23, v26, v22
	v_sub_f32_e32 v26, v23, v26
	v_add_f32_e32 v27, v32, v23
	v_sub_f32_e32 v22, v22, v26
	v_sub_f32_e32 v26, v27, v32
	v_sub_f32_e32 v28, v27, v26
	v_sub_f32_e32 v23, v23, v26
	v_add_f32_e32 v26, v25, v22
	v_sub_f32_e32 v28, v32, v28
	v_sub_f32_e32 v29, v26, v25
	v_add_f32_e32 v23, v23, v28
	v_sub_f32_e32 v28, v26, v29
	v_sub_f32_e32 v22, v22, v29
	v_sub_f32_e32 v25, v25, v28
	v_add_f32_e32 v23, v26, v23
	v_add_f32_e32 v22, v22, v25
	v_add_f32_e32 v25, v27, v23
	v_sub_f32_e32 v26, v25, v27
	v_sub_f32_e32 v23, v23, v26
	v_add_f32_e32 v22, v22, v23
	v_add_f32_e32 v22, v25, v22
	v_cmp_neq_f32_e64 s[0:1], s23, v24
	s_nop 1
	v_cndmask_b32_e64 v22, v17, v22, s[0:1]
	v_cmp_ngt_f32_e64 s[0:1], -1.0, v24
	s_nop 1
	v_cndmask_b32_e64 v22, v18, v22, s[0:1]
	v_cmp_neq_f32_e64 s[0:1], -1.0, v24
	s_nop 1
	v_cndmask_b32_e64 v22, v19, v22, s[0:1]
	v_cmp_lt_f32_e64 s[0:1], |v24|, s33
	s_nop 1
	v_cndmask_b32_e64 v22, v22, v24, s[0:1]
	v_sub_f32_e32 v21, v21, v22
	v_mul_f32_e32 v22, 0x3fb8aa3b, v21
	ds_bpermute_b32 v23, v10, v22
	s_or_b32 s0, s22, 2
	s_ashr_i32 s1, s0, 31
	s_lshl_b64 s[28:29], s[0:1], 14
	v_lshl_or_b32 v24, v12, 2, s28
	s_waitcnt lgkmcnt(0)
	v_fmac_f32_e32 v23, 0x3fb8aa3b, v21
	v_cndmask_b32_e64 v21, v23, v22, s[2:3]
	ds_bpermute_b32 v22, v11, v21
	v_mov_b32_e32 v25, s29
	v_lshl_add_u64 v[26:27], s[20:21], 0, v[24:25]
	v_lshl_add_u64 v[24:25], s[26:27], 0, v[24:25]
	s_waitcnt lgkmcnt(0)
	v_add_f32_e32 v22, v21, v22
	v_cndmask_b32_e64 v21, v22, v21, s[8:9]
	ds_bpermute_b32 v22, v13, v21
	s_waitcnt lgkmcnt(0)
	v_add_f32_e32 v22, v21, v22
	v_cndmask_b32_e64 v21, v22, v21, s[10:11]
	ds_bpermute_b32 v22, v14, v21
	s_waitcnt lgkmcnt(0)
	v_add_f32_e32 v22, v21, v22
	v_cndmask_b32_e64 v22, v22, v21, s[6:7]
	ds_bpermute_b32 v23, v15, v22
	v_mov_b32_e32 v21, 0x3f2aaada
	s_waitcnt lgkmcnt(0)
	v_add_f32_e32 v23, v22, v23
	v_cndmask_b32_e64 v23, v23, v22, s[12:13]
	ds_bpermute_b32 v22, v16, v23
	s_waitcnt lgkmcnt(0)
	v_add_f32_e32 v22, v23, v22
	v_cndmask_b32_e64 v23, v22, v23, s[4:5]
	global_store_dword v[26:27], v23, off
	v_xor_b32_e32 v23, 0x80000000, v23
	global_store_dword v[24:25], v23, off
	s_and_saveexec_b64 s[28:29], vcc
	s_cbranch_execz .LBB0_459
	s_lshl_b32 s0, s0, 6
	s_or_b32 s0, s0, s15
	s_ashr_i32 s1, s0, 31
	s_lshl_b64 s[0:1], s[0:1], 2
	s_add_u32 s0, s30, s0
	s_addc_u32 s1, s31, s1
	global_store_dword v20, v22, s[0:1]
; __global__ void __launch_bounds__(512, 2) fwd_kernel(Args a) {
;     ...
;             for (int hh = 0; hh < 16; ++hh) { const float z = fz[hh] + bfp[hh]; float incl = (fminf(z, 0.f) - log1pf(__expf(-fabsf(z)))) * LOG2E;
; #pragma unroll
;                 for (int o = 1; o < 64; o <<= 1) { const float t = __shfl_up(incl, o); if (lane >= o) incl += t; }
;                 cum[(size_t)(b * 16 + hh) * SEQ + ch * 64 + lane] = incl; ((float*)(ws + WS_NCUM))[(size_t)(b * 16 + hh) * SEQ + ch * 64 + lane] = -incl;
;                 if (lane == 63) totp[(b * 16 + hh) * 64 + ch] = incl; }
.LBB0_459:
	s_or_b64 exec, exec, s[28:29]
	v_mov_b32_e32 v20, v43
	v_and_b32_e32 v7, 0xffff0000, v7
	v_add_f32_e32 v7, v20, v7
	v_mul_f32_e64 v20, |v7|, s36
	v_exp_f32_e32 v20, v20
	v_min_f32_e32 v7, 0, v7
	v_add_f32_e32 v24, 1.0, v20
	v_add_f32_e32 v25, -1.0, v24
	v_frexp_mant_f32_e32 v26, v24
	v_cvt_f64_f32_e32 v[22:23], v24
	v_sub_f32_e32 v27, v25, v24
	v_frexp_exp_i32_f64_e32 v22, v[22:23]
	v_cmp_gt_f32_e64 s[0:1], s35, v26
	v_sub_f32_e32 v25, v20, v25
	v_add_f32_e32 v23, 1.0, v27
	v_subbrev_co_u32_e64 v22, s[0:1], 0, v22, s[0:1]
	v_add_f32_e32 v23, v25, v23
	v_sub_u32_e32 v25, 0, v22
	v_cvt_f32_i32_e32 v22, v22
	v_ldexp_f32 v24, v24, v25
	v_ldexp_f32 v23, v23, v25
	v_add_f32_e32 v25, -1.0, v24
	v_add_f32_e32 v26, 1.0, v24
	v_add_f32_e32 v27, 1.0, v25
	v_add_f32_e32 v28, -1.0, v26
	v_sub_f32_e32 v27, v24, v27
	v_sub_f32_e32 v24, v24, v28
	v_mul_f32_e32 v28, 0x3f317218, v22
	v_add_f32_e32 v27, v23, v27
	v_add_f32_e32 v23, v23, v24
	v_fma_f32 v24, v22, s34, -v28
	v_add_f32_e32 v29, v25, v27
	v_add_f32_e32 v30, v26, v23
	v_fmac_f32_e32 v24, 0xb102e308, v22
	v_sub_f32_e32 v22, v29, v25
	v_sub_f32_e32 v25, v30, v26
	v_rcp_f32_e32 v26, v30
	v_add_f32_e32 v31, v28, v24
	v_sub_f32_e32 v23, v23, v25
	v_sub_f32_e32 v25, v31, v28
	v_sub_f32_e32 v24, v24, v25
	v_mul_f32_e32 v25, v29, v26
	v_sub_f32_e32 v22, v27, v22
	v_mul_f32_e32 v27, v30, v25
	v_fma_f32 v28, v25, v30, -v27
	v_fmac_f32_e32 v28, v25, v23
	v_add_f32_e32 v32, v27, v28
	v_sub_f32_e32 v33, v29, v32
	v_sub_f32_e32 v27, v32, v27
	v_sub_f32_e32 v29, v29, v33
	v_sub_f32_e32 v27, v27, v28
	v_sub_f32_e32 v28, v29, v32
	v_add_f32_e32 v22, v22, v28
	v_add_f32_e32 v22, v27, v22
	v_add_f32_e32 v27, v33, v22
	v_mul_f32_e32 v28, v26, v27
	v_sub_f32_e32 v29, v33, v27
	v_mul_f32_e32 v32, v30, v28
	v_add_f32_e32 v22, v22, v29
	v_add_f32_e32 v29, v25, v28
	v_fma_f32 v30, v28, v30, -v32
	v_sub_f32_e32 v25, v29, v25
	v_fmac_f32_e32 v30, v28, v23
	v_sub_f32_e32 v23, v28, v25
	v_add_f32_e32 v25, v32, v30
	v_sub_f32_e32 v28, v25, v32
	v_sub_f32_e32 v32, v27, v25
	v_sub_f32_e32 v27, v27, v32
	v_sub_f32_e32 v25, v27, v25
	v_sub_f32_e32 v28, v28, v30
	v_add_f32_e32 v22, v22, v25
	v_add_f32_e32 v22, v28, v22
	v_add_f32_e32 v22, v32, v22
	v_mul_f32_e32 v22, v26, v22
	v_add_f32_e32 v22, v23, v22
	v_add_f32_e32 v23, v29, v22
	v_mul_f32_e32 v25, v23, v23
	v_fmac_f32_e32 v6, 0x3e9b6dac, v25
	v_sub_f32_e32 v26, v23, v29
	v_ldexp_f32 v27, v23, 1
	v_mul_f32_e32 v23, v23, v25
	v_fmac_f32_e32 v21, v25, v6
	v_sub_f32_e32 v22, v22, v26
	v_mul_f32_e32 v21, v23, v21
	v_ldexp_f32 v6, v22, 1
	v_add_f32_e32 v22, v27, v21
	v_sub_f32_e32 v23, v22, v27
	v_sub_f32_e32 v21, v21, v23
	v_add_f32_e32 v6, v6, v21
	v_add_f32_e32 v21, v22, v6
	v_sub_f32_e32 v22, v21, v22
	v_add_f32_e32 v23, v31, v21
	v_sub_f32_e32 v6, v6, v22
	v_sub_f32_e32 v22, v23, v31
	v_sub_f32_e32 v25, v23, v22
	v_sub_f32_e32 v21, v21, v22
	v_sub_f32_e32 v25, v31, v25
	v_add_f32_e32 v22, v24, v6
	v_add_f32_e32 v21, v21, v25
	v_sub_f32_e32 v26, v22, v24
	v_add_f32_e32 v21, v22, v21
	v_sub_f32_e32 v25, v22, v26
	v_add_f32_e32 v22, v23, v21
	v_sub_f32_e32 v6, v6, v26
	v_sub_f32_e32 v24, v24, v25
	v_sub_f32_e32 v23, v22, v23
	v_add_f32_e32 v6, v6, v24
	v_sub_f32_e32 v21, v21, v23
	v_add_f32_e32 v6, v6, v21
	v_add_f32_e32 v6, v22, v6
	v_cmp_neq_f32_e64 s[0:1], s23, v20
	s_nop 1
	v_cndmask_b32_e64 v6, v17, v6, s[0:1]
	v_cmp_ngt_f32_e64 s[0:1], -1.0, v20
	s_nop 1
	v_cndmask_b32_e64 v6, v18, v6, s[0:1]
	v_cmp_neq_f32_e64 s[0:1], -1.0, v20
	s_nop 1
	v_cndmask_b32_e64 v6, v19, v6, s[0:1]
	v_cmp_lt_f32_e64 s[0:1], |v20|, s33
	s_nop 1
	v_cndmask_b32_e64 v6, v6, v20, s[0:1]
	v_sub_f32_e32 v6, v7, v6
	v_mul_f32_e32 v7, 0x3fb8aa3b, v6
	ds_bpermute_b32 v17, v10, v7
	s_or_b32 s0, s22, 3
	s_ashr_i32 s1, s0, 31
	s_lshl_b64 s[28:29], s[0:1], 14
	v_lshl_or_b32 v18, v12, 2, s28
	s_waitcnt lgkmcnt(0)
	v_fmac_f32_e32 v17, 0x3fb8aa3b, v6
	v_cndmask_b32_e64 v6, v17, v7, s[2:3]
	ds_bpermute_b32 v7, v11, v6
	v_mov_b32_e32 v19, s29
	v_lshl_add_u64 v[20:21], s[20:21], 0, v[18:19]
	v_lshl_add_u64 v[18:19], s[26:27], 0, v[18:19]
	s_waitcnt lgkmcnt(0)
	v_add_f32_e32 v7, v6, v7
	v_cndmask_b32_e64 v6, v7, v6, s[8:9]
	ds_bpermute_b32 v7, v13, v6
	s_waitcnt lgkmcnt(0)
	v_add_f32_e32 v7, v6, v7
	v_cndmask_b32_e64 v6, v7, v6, s[10:11]
	ds_bpermute_b32 v7, v14, v6
	s_waitcnt lgkmcnt(0)
	v_add_f32_e32 v7, v6, v7
	v_cndmask_b32_e64 v6, v7, v6, s[6:7]
	ds_bpermute_b32 v7, v15, v6
	s_waitcnt lgkmcnt(0)
	v_add_f32_e32 v7, v6, v7
	v_cndmask_b32_e64 v7, v7, v6, s[12:13]
	ds_bpermute_b32 v6, v16, v7
	s_waitcnt lgkmcnt(0)
	v_add_f32_e32 v6, v7, v6
	v_cndmask_b32_e64 v7, v6, v7, s[4:5]
	global_store_dword v[20:21], v7, off
	v_xor_b32_e32 v7, 0x80000000, v7
	global_store_dword v[18:19], v7, off
	s_and_saveexec_b64 s[28:29], vcc
	s_cbranch_execz .LBB0_461
	s_lshl_b32 s0, s0, 6
	s_or_b32 s0, s0, s15
	s_ashr_i32 s1, s0, 31
	s_lshl_b64 s[0:1], s[0:1], 2
	s_add_u32 s0, s30, s0
	s_addc_u32 s1, s31, s1
	v_mov_b32_e32 v7, 0
	global_store_dword v7, v6, s[0:1]
; __global__ void __launch_bounds__(512, 2) fwd_kernel(Args a) {
;     ...
;             for (int hh = 0; hh < 16; ++hh) { const float z = fz[hh] + bfp[hh]; float incl = (fminf(z, 0.f) - log1pf(__expf(-fabsf(z)))) * LOG2E;
; #pragma unroll
;                 for (int o = 1; o < 64; o <<= 1) { const float t = __shfl_up(incl, o); if (lane >= o) incl += t; }
;                 cum[(size_t)(b * 16 + hh) * SEQ + ch * 64 + lane] = incl; ((float*)(ws + WS_NCUM))[(size_t)(b * 16 + hh) * SEQ + ch * 64 + lane] = -incl;
;                 if (lane == 63) totp[(b * 16 + hh) * 64 + ch] = incl; }
.LBB0_461:
	s_or_b64 exec, exec, s[28:29]
	v_mov_b32_e32 v19, 0
	v_mov_b32_e32 v18, v44
	v_lshlrev_b32_e32 v20, 16, v8
	v_mov_b32_e32 v6, 0x3ecc95a3
	v_mov_b32_e32 v7, 0x7f800000
	v_mov_b32_e32 v17, 0x7fc00000
	v_add_f32_e32 v20, v18, v20
	v_mul_f32_e64 v18, |v20|, s36
	v_exp_f32_e32 v22, v18
	v_min_f32_e32 v23, 0, v20
	v_mov_b32_e32 v18, 0xff800000
	v_add_f32_e32 v24, 1.0, v22
	v_add_f32_e32 v25, -1.0, v24
	v_frexp_mant_f32_e32 v26, v24
	v_cvt_f64_f32_e32 v[20:21], v24
	v_sub_f32_e32 v27, v25, v24
	v_frexp_exp_i32_f64_e32 v20, v[20:21]
	v_cmp_gt_f32_e64 s[0:1], s35, v26
	v_sub_f32_e32 v25, v22, v25
	v_add_f32_e32 v21, 1.0, v27
	v_subbrev_co_u32_e64 v20, s[0:1], 0, v20, s[0:1]
	v_add_f32_e32 v21, v25, v21
	v_sub_u32_e32 v25, 0, v20
	v_cvt_f32_i32_e32 v20, v20
	v_ldexp_f32 v24, v24, v25
	v_ldexp_f32 v21, v21, v25
	v_add_f32_e32 v25, -1.0, v24
	v_add_f32_e32 v26, 1.0, v24
	v_add_f32_e32 v27, 1.0, v25
	v_add_f32_e32 v28, -1.0, v26
	v_sub_f32_e32 v27, v24, v27
	v_sub_f32_e32 v24, v24, v28
	v_mul_f32_e32 v28, 0x3f317218, v20
	v_add_f32_e32 v27, v21, v27
	v_add_f32_e32 v21, v21, v24
	v_fma_f32 v24, v20, s34, -v28
	v_add_f32_e32 v29, v25, v27
	v_add_f32_e32 v30, v26, v21
	v_fmac_f32_e32 v24, 0xb102e308, v20
	v_sub_f32_e32 v20, v29, v25
	v_sub_f32_e32 v25, v30, v26
	v_rcp_f32_e32 v26, v30
	v_add_f32_e32 v31, v28, v24
	v_sub_f32_e32 v21, v21, v25
	v_sub_f32_e32 v25, v31, v28
	v_sub_f32_e32 v24, v24, v25
	v_mul_f32_e32 v25, v29, v26
	v_sub_f32_e32 v20, v27, v20
	v_mul_f32_e32 v27, v30, v25
	v_fma_f32 v28, v25, v30, -v27
	v_fmac_f32_e32 v28, v25, v21
	v_add_f32_e32 v32, v27, v28
	v_sub_f32_e32 v33, v29, v32
	v_sub_f32_e32 v27, v32, v27
	v_sub_f32_e32 v29, v29, v33
	v_sub_f32_e32 v27, v27, v28
	v_sub_f32_e32 v28, v29, v32
	v_add_f32_e32 v20, v20, v28
	v_add_f32_e32 v20, v27, v20
	v_add_f32_e32 v27, v33, v20
	v_mul_f32_e32 v28, v26, v27
	v_sub_f32_e32 v29, v33, v27
	v_mul_f32_e32 v32, v30, v28
	v_add_f32_e32 v20, v20, v29
	v_add_f32_e32 v29, v25, v28
	v_fma_f32 v30, v28, v30, -v32
	v_sub_f32_e32 v25, v29, v25
	v_fmac_f32_e32 v30, v28, v21
	v_sub_f32_e32 v21, v28, v25
	v_add_f32_e32 v25, v32, v30
	v_sub_f32_e32 v28, v25, v32
	v_sub_f32_e32 v32, v27, v25
	v_sub_f32_e32 v27, v27, v32
	v_sub_f32_e32 v25, v27, v25
	v_sub_f32_e32 v28, v28, v30
	v_add_f32_e32 v20, v20, v25
	v_add_f32_e32 v20, v28, v20
	v_add_f32_e32 v20, v32, v20
	v_mul_f32_e32 v20, v26, v20
	v_add_f32_e32 v20, v21, v20
	v_add_f32_e32 v21, v29, v20
	v_mul_f32_e32 v25, v21, v21
	v_fmamk_f32 v28, v25, 0x3e9b6dac, v6
	v_sub_f32_e32 v26, v21, v29
	v_ldexp_f32 v27, v21, 1
	v_mul_f32_e32 v21, v21, v25
	v_fmaak_f32 v25, v25, v28, 0x3f2aaada
	v_mul_f32_e32 v21, v21, v25
	v_add_f32_e32 v25, v27, v21
	v_sub_f32_e32 v20, v20, v26
	v_sub_f32_e32 v26, v25, v27
	v_ldexp_f32 v20, v20, 1
	v_sub_f32_e32 v21, v21, v26
	v_add_f32_e32 v20, v20, v21
	v_add_f32_e32 v21, v25, v20
	v_sub_f32_e32 v25, v21, v25
	v_add_f32_e32 v26, v31, v21
	v_sub_f32_e32 v20, v20, v25
	v_sub_f32_e32 v25, v26, v31
	v_sub_f32_e32 v27, v26, v25
	v_sub_f32_e32 v21, v21, v25
	v_add_f32_e32 v25, v24, v20
	v_sub_f32_e32 v27, v31, v27
	v_sub_f32_e32 v28, v25, v24
	v_add_f32_e32 v21, v21, v27
	v_sub_f32_e32 v27, v25, v28
	v_sub_f32_e32 v20, v20, v28
	v_sub_f32_e32 v24, v24, v27
	v_add_f32_e32 v21, v25, v21
	v_add_f32_e32 v20, v20, v24
	v_add_f32_e32 v24, v26, v21
	v_sub_f32_e32 v25, v24, v26
	v_sub_f32_e32 v21, v21, v25
	v_add_f32_e32 v20, v20, v21
	v_add_f32_e32 v20, v24, v20
	v_cmp_neq_f32_e64 s[0:1], s23, v22
	s_nop 1
	v_cndmask_b32_e64 v20, v7, v20, s[0:1]
	v_cmp_ngt_f32_e64 s[0:1], -1.0, v22
	s_nop 1
	v_cndmask_b32_e64 v20, v17, v20, s[0:1]
	v_cmp_neq_f32_e64 s[0:1], -1.0, v22
	s_nop 1
	v_cndmask_b32_e64 v20, v18, v20, s[0:1]
	v_cmp_lt_f32_e64 s[0:1], |v22|, s33
	s_nop 1
	v_cndmask_b32_e64 v20, v20, v22, s[0:1]
	v_sub_f32_e32 v20, v23, v20
	v_mul_f32_e32 v21, 0x3fb8aa3b, v20
	ds_bpermute_b32 v22, v10, v21
	s_or_b32 s0, s22, 4
	s_ashr_i32 s1, s0, 31
	s_lshl_b64 s[28:29], s[0:1], 14
	v_mov_b32_e32 v23, s29
	s_waitcnt lgkmcnt(0)
	v_fmac_f32_e32 v22, 0x3fb8aa3b, v20
	v_cndmask_b32_e64 v20, v22, v21, s[2:3]
	ds_bpermute_b32 v21, v11, v20
	s_waitcnt lgkmcnt(0)
	v_add_f32_e32 v21, v20, v21
	v_cndmask_b32_e64 v20, v21, v20, s[8:9]
	ds_bpermute_b32 v21, v13, v20
	s_waitcnt lgkmcnt(0)
	v_add_f32_e32 v21, v20, v21
	v_cndmask_b32_e64 v20, v21, v20, s[10:11]
	ds_bpermute_b32 v21, v14, v20
	s_waitcnt lgkmcnt(0)
	v_add_f32_e32 v21, v20, v21
	v_cndmask_b32_e64 v21, v21, v20, s[6:7]
	ds_bpermute_b32 v22, v15, v21
	v_mov_b32_e32 v20, 0x3f2aaada
	s_waitcnt lgkmcnt(0)
	v_add_f32_e32 v22, v21, v22
	v_cndmask_b32_e64 v26, v22, v21, s[12:13]
	ds_bpermute_b32 v21, v16, v26
	v_lshl_or_b32 v22, v12, 2, s28
	v_lshl_add_u64 v[24:25], s[20:21], 0, v[22:23]
	v_lshl_add_u64 v[22:23], s[26:27], 0, v[22:23]
	s_waitcnt lgkmcnt(0)
	v_add_f32_e32 v21, v26, v21
	v_cndmask_b32_e64 v26, v21, v26, s[4:5]
	global_store_dword v[24:25], v26, off
	v_xor_b32_e32 v24, 0x80000000, v26
	global_store_dword v[22:23], v24, off
	s_and_saveexec_b64 s[28:29], vcc
	s_cbranch_execz .LBB0_463
	s_lshl_b32 s0, s0, 6
	s_or_b32 s0, s0, s15
	s_ashr_i32 s1, s0, 31
	s_lshl_b64 s[0:1], s[0:1], 2
	s_add_u32 s0, s30, s0
	s_addc_u32 s1, s31, s1
	global_store_dword v19, v21, s[0:1]
; __global__ void __launch_bounds__(512, 2) fwd_kernel(Args a) {
;     ...
;             for (int hh = 0; hh < 16; ++hh) { const float z = fz[hh] + bfp[hh]; float incl = (fminf(z, 0.f) - log1pf(__expf(-fabsf(z)))) * LOG2E;
; #pragma unroll
;                 for (int o = 1; o < 64; o <<= 1) { const float t = __shfl_up(incl, o); if (lane >= o) incl += t; }
;                 cum[(size_t)(b * 16 + hh) * SEQ + ch * 64 + lane] = incl; ((float*)(ws + WS_NCUM))[(size_t)(b * 16 + hh) * SEQ + ch * 64 + lane] = -incl;
;                 if (lane == 63) totp[(b * 16 + hh) * 64 + ch] = incl; }
.LBB0_463:
	s_or_b64 exec, exec, s[28:29]
	v_mov_b32_e32 v19, v45
	v_and_b32_e32 v8, 0xffff0000, v8
	v_add_f32_e32 v8, v19, v8
	v_mul_f32_e64 v19, |v8|, s36
	v_exp_f32_e32 v19, v19
	v_min_f32_e32 v8, 0, v8
	v_add_f32_e32 v21, 1.0, v19
	v_add_f32_e32 v24, -1.0, v21
	v_frexp_mant_f32_e32 v25, v21
	v_cvt_f64_f32_e32 v[22:23], v21
	v_sub_f32_e32 v26, v24, v21
	v_frexp_exp_i32_f64_e32 v22, v[22:23]
	v_cmp_gt_f32_e64 s[0:1], s35, v25
	v_sub_f32_e32 v24, v19, v24
	v_add_f32_e32 v23, 1.0, v26
	v_subbrev_co_u32_e64 v22, s[0:1], 0, v22, s[0:1]
	v_add_f32_e32 v23, v24, v23
	v_sub_u32_e32 v24, 0, v22
	v_cvt_f32_i32_e32 v22, v22
	v_ldexp_f32 v21, v21, v24
	v_ldexp_f32 v23, v23, v24
	v_add_f32_e32 v24, -1.0, v21
	v_add_f32_e32 v25, 1.0, v21
	v_add_f32_e32 v26, 1.0, v24
	v_add_f32_e32 v27, -1.0, v25
	v_sub_f32_e32 v26, v21, v26
	v_sub_f32_e32 v21, v21, v27
	v_mul_f32_e32 v27, 0x3f317218, v22
	v_add_f32_e32 v26, v23, v26
	v_add_f32_e32 v21, v23, v21
	v_fma_f32 v23, v22, s34, -v27
	v_add_f32_e32 v28, v24, v26
	v_add_f32_e32 v29, v25, v21
	v_fmac_f32_e32 v23, 0xb102e308, v22
	v_sub_f32_e32 v22, v28, v24
	v_sub_f32_e32 v24, v29, v25
	v_rcp_f32_e32 v25, v29
	v_add_f32_e32 v30, v27, v23
	v_sub_f32_e32 v21, v21, v24
	v_sub_f32_e32 v24, v30, v27
	v_sub_f32_e32 v23, v23, v24
	v_mul_f32_e32 v24, v28, v25
	v_sub_f32_e32 v22, v26, v22
	v_mul_f32_e32 v26, v29, v24
	v_fma_f32 v27, v24, v29, -v26
	v_fmac_f32_e32 v27, v24, v21
	v_add_f32_e32 v31, v26, v27
	v_sub_f32_e32 v32, v28, v31
	v_sub_f32_e32 v26, v31, v26
	v_sub_f32_e32 v28, v28, v32
	v_sub_f32_e32 v26, v26, v27
	v_sub_f32_e32 v27, v28, v31
	v_add_f32_e32 v22, v22, v27
	v_add_f32_e32 v22, v26, v22
	v_add_f32_e32 v26, v32, v22
	v_mul_f32_e32 v27, v25, v26
	v_sub_f32_e32 v28, v32, v26
	v_mul_f32_e32 v31, v29, v27
	v_add_f32_e32 v22, v22, v28
	v_add_f32_e32 v28, v24, v27
	v_fma_f32 v29, v27, v29, -v31
	v_sub_f32_e32 v24, v28, v24
	v_fmac_f32_e32 v29, v27, v21
	v_sub_f32_e32 v21, v27, v24
	v_add_f32_e32 v24, v31, v29
	v_sub_f32_e32 v27, v24, v31
	v_sub_f32_e32 v31, v26, v24
	v_sub_f32_e32 v26, v26, v31
	v_sub_f32_e32 v24, v26, v24
	v_sub_f32_e32 v27, v27, v29
	v_add_f32_e32 v22, v22, v24
	v_add_f32_e32 v22, v27, v22
	v_add_f32_e32 v22, v31, v22
	v_mul_f32_e32 v22, v25, v22
	v_add_f32_e32 v21, v21, v22
	v_add_f32_e32 v22, v28, v21
	v_mul_f32_e32 v24, v22, v22
	v_fmac_f32_e32 v6, 0x3e9b6dac, v24
	v_sub_f32_e32 v25, v22, v28
	v_ldexp_f32 v26, v22, 1
	v_mul_f32_e32 v22, v22, v24
	v_fmac_f32_e32 v20, v24, v6
	v_sub_f32_e32 v21, v21, v25
	v_mul_f32_e32 v20, v22, v20
	v_ldexp_f32 v6, v21, 1
	v_add_f32_e32 v21, v26, v20
	v_sub_f32_e32 v22, v21, v26
	v_sub_f32_e32 v20, v20, v22
	v_add_f32_e32 v6, v6, v20
	v_add_f32_e32 v20, v21, v6
	v_sub_f32_e32 v21, v20, v21
	v_add_f32_e32 v22, v30, v20
	v_sub_f32_e32 v6, v6, v21
	v_sub_f32_e32 v21, v22, v30
	v_sub_f32_e32 v24, v22, v21
	v_sub_f32_e32 v20, v20, v21
	v_sub_f32_e32 v24, v30, v24
	v_add_f32_e32 v21, v23, v6
	v_add_f32_e32 v20, v20, v24
	v_sub_f32_e32 v25, v21, v23
	v_add_f32_e32 v20, v21, v20
	v_sub_f32_e32 v24, v21, v25
	v_add_f32_e32 v21, v22, v20
	v_sub_f32_e32 v6, v6, v25
	v_sub_f32_e32 v23, v23, v24
	v_sub_f32_e32 v22, v21, v22
	v_add_f32_e32 v6, v6, v23
	v_sub_f32_e32 v20, v20, v22
	v_add_f32_e32 v6, v6, v20
	v_add_f32_e32 v6, v21, v6
	v_cmp_neq_f32_e64 s[0:1], s23, v19
	s_nop 1
	v_cndmask_b32_e64 v6, v7, v6, s[0:1]
	v_cmp_ngt_f32_e64 s[0:1], -1.0, v19
	s_nop 1
	v_cndmask_b32_e64 v6, v17, v6, s[0:1]
	v_cmp_neq_f32_e64 s[0:1], -1.0, v19
	s_nop 1
	v_cndmask_b32_e64 v6, v18, v6, s[0:1]
	v_cmp_lt_f32_e64 s[0:1], |v19|, s33
	s_nop 1
	v_cndmask_b32_e64 v6, v6, v19, s[0:1]
	v_sub_f32_e32 v6, v8, v6
	v_mul_f32_e32 v7, 0x3fb8aa3b, v6
	ds_bpermute_b32 v8, v10, v7
	s_or_b32 s0, s22, 5
	s_ashr_i32 s1, s0, 31
	s_lshl_b64 s[28:29], s[0:1], 14
	v_lshl_or_b32 v18, v12, 2, s28
	s_waitcnt lgkmcnt(0)
	v_fmac_f32_e32 v8, 0x3fb8aa3b, v6
	v_cndmask_b32_e64 v6, v8, v7, s[2:3]
	ds_bpermute_b32 v7, v11, v6
	v_mov_b32_e32 v19, s29
	v_lshl_add_u64 v[20:21], s[20:21], 0, v[18:19]
	v_lshl_add_u64 v[18:19], s[26:27], 0, v[18:19]
	s_waitcnt lgkmcnt(0)
	v_add_f32_e32 v7, v6, v7
	v_cndmask_b32_e64 v6, v7, v6, s[8:9]
	ds_bpermute_b32 v7, v13, v6
	s_waitcnt lgkmcnt(0)
	v_add_f32_e32 v7, v6, v7
	v_cndmask_b32_e64 v6, v7, v6, s[10:11]
	ds_bpermute_b32 v7, v14, v6
	s_waitcnt lgkmcnt(0)
	v_add_f32_e32 v7, v6, v7
	v_cndmask_b32_e64 v6, v7, v6, s[6:7]
	ds_bpermute_b32 v7, v15, v6
	s_waitcnt lgkmcnt(0)
	v_add_f32_e32 v7, v6, v7
	v_cndmask_b32_e64 v7, v7, v6, s[12:13]
	ds_bpermute_b32 v6, v16, v7
	s_waitcnt lgkmcnt(0)
	v_add_f32_e32 v6, v7, v6
	v_cndmask_b32_e64 v7, v6, v7, s[4:5]
	global_store_dword v[20:21], v7, off
	v_xor_b32_e32 v7, 0x80000000, v7
	global_store_dword v[18:19], v7, off
	s_and_saveexec_b64 s[28:29], vcc
	s_cbranch_execz .LBB0_465
	s_lshl_b32 s0, s0, 6
	s_or_b32 s0, s0, s15
	s_ashr_i32 s1, s0, 31
	s_lshl_b64 s[0:1], s[0:1], 2
	s_add_u32 s0, s30, s0
	s_addc_u32 s1, s31, s1
	v_mov_b32_e32 v7, 0
	global_store_dword v7, v6, s[0:1]
; __global__ void __launch_bounds__(512, 2) fwd_kernel(Args a) {
;     ...
;             for (int hh = 0; hh < 16; ++hh) { const float z = fz[hh] + bfp[hh]; float incl = (fminf(z, 0.f) - log1pf(__expf(-fabsf(z)))) * LOG2E;
; #pragma unroll
;                 for (int o = 1; o < 64; o <<= 1) { const float t = __shfl_up(incl, o); if (lane >= o) incl += t; }
;                 cum[(size_t)(b * 16 + hh) * SEQ + ch * 64 + lane] = incl; ((float*)(ws + WS_NCUM))[(size_t)(b * 16 + hh) * SEQ + ch * 64 + lane] = -incl;
;                 if (lane == 63) totp[(b * 16 + hh) * 64 + ch] = incl; }
.LBB0_465:
	s_or_b64 exec, exec, s[28:29]
	v_mov_b32_e32 v18, 0
	v_mov_b32_e32 v17, v46
	v_lshlrev_b32_e32 v19, 16, v9
	v_mov_b32_e32 v6, 0x3ecc95a3
	v_mov_b32_e32 v7, 0x7f800000
	v_mov_b32_e32 v8, 0x7fc00000
	v_add_f32_e32 v19, v17, v19
	v_mul_f32_e64 v17, |v19|, s36
	v_exp_f32_e32 v22, v17
	v_mov_b32_e32 v17, 0xff800000
	v_min_f32_e32 v19, 0, v19
	v_add_f32_e32 v23, 1.0, v22
	v_add_f32_e32 v24, -1.0, v23
	v_frexp_mant_f32_e32 v25, v23
	v_cvt_f64_f32_e32 v[20:21], v23
	v_sub_f32_e32 v26, v24, v23
	v_frexp_exp_i32_f64_e32 v20, v[20:21]
	v_cmp_gt_f32_e64 s[0:1], s35, v25
	v_sub_f32_e32 v24, v22, v24
	v_add_f32_e32 v21, 1.0, v26
	v_subbrev_co_u32_e64 v20, s[0:1], 0, v20, s[0:1]
	v_add_f32_e32 v21, v24, v21
	v_sub_u32_e32 v24, 0, v20
	v_cvt_f32_i32_e32 v20, v20
	v_ldexp_f32 v23, v23, v24
	v_ldexp_f32 v21, v21, v24
	v_add_f32_e32 v24, -1.0, v23
	v_add_f32_e32 v25, 1.0, v23
	v_add_f32_e32 v26, 1.0, v24
	v_add_f32_e32 v27, -1.0, v25
	v_sub_f32_e32 v26, v23, v26
	v_sub_f32_e32 v23, v23, v27
	v_mul_f32_e32 v27, 0x3f317218, v20
	v_add_f32_e32 v26, v21, v26
	v_add_f32_e32 v21, v21, v23
	v_fma_f32 v23, v20, s34, -v27
	v_add_f32_e32 v28, v24, v26
	v_add_f32_e32 v29, v25, v21
	v_fmac_f32_e32 v23, 0xb102e308, v20
	v_sub_f32_e32 v20, v28, v24
	v_sub_f32_e32 v24, v29, v25
	v_rcp_f32_e32 v25, v29
	v_add_f32_e32 v30, v27, v23
	v_sub_f32_e32 v21, v21, v24
	v_sub_f32_e32 v24, v30, v27
	v_sub_f32_e32 v23, v23, v24
	v_mul_f32_e32 v24, v28, v25
	v_sub_f32_e32 v20, v26, v20
	v_mul_f32_e32 v26, v29, v24
	v_fma_f32 v27, v24, v29, -v26
	v_fmac_f32_e32 v27, v24, v21
	v_add_f32_e32 v31, v26, v27
	v_sub_f32_e32 v32, v28, v31
	v_sub_f32_e32 v26, v31, v26
	v_sub_f32_e32 v28, v28, v32
	v_sub_f32_e32 v26, v26, v27
	v_sub_f32_e32 v27, v28, v31
	v_add_f32_e32 v20, v20, v27
	v_add_f32_e32 v20, v26, v20
	v_add_f32_e32 v26, v32, v20
	v_mul_f32_e32 v27, v25, v26
	v_sub_f32_e32 v28, v32, v26
	v_mul_f32_e32 v31, v29, v27
	v_add_f32_e32 v20, v20, v28
	v_add_f32_e32 v28, v24, v27
	v_fma_f32 v29, v27, v29, -v31
	v_sub_f32_e32 v24, v28, v24
	v_fmac_f32_e32 v29, v27, v21
	v_sub_f32_e32 v21, v27, v24
	v_add_f32_e32 v24, v31, v29
	v_sub_f32_e32 v27, v24, v31
	v_sub_f32_e32 v31, v26, v24
	v_sub_f32_e32 v26, v26, v31
	v_sub_f32_e32 v24, v26, v24
	v_sub_f32_e32 v27, v27, v29
	v_add_f32_e32 v20, v20, v24
	v_add_f32_e32 v20, v27, v20
	v_add_f32_e32 v20, v31, v20
	v_mul_f32_e32 v20, v25, v20
	v_add_f32_e32 v20, v21, v20
	v_add_f32_e32 v21, v28, v20
	v_mul_f32_e32 v24, v21, v21
	v_fmamk_f32 v27, v24, 0x3e9b6dac, v6
	v_sub_f32_e32 v25, v21, v28
	v_ldexp_f32 v26, v21, 1
	v_mul_f32_e32 v21, v21, v24
	v_fmaak_f32 v24, v24, v27, 0x3f2aaada
	v_mul_f32_e32 v21, v21, v24
	v_add_f32_e32 v24, v26, v21
	v_sub_f32_e32 v20, v20, v25
	v_sub_f32_e32 v25, v24, v26
	v_ldexp_f32 v20, v20, 1
	v_sub_f32_e32 v21, v21, v25
	v_add_f32_e32 v20, v20, v21
	v_add_f32_e32 v21, v24, v20
	v_sub_f32_e32 v24, v21, v24
	v_add_f32_e32 v25, v30, v21
	v_sub_f32_e32 v20, v20, v24
	v_sub_f32_e32 v24, v25, v30
	v_sub_f32_e32 v26, v25, v24
	v_sub_f32_e32 v21, v21, v24
	v_add_f32_e32 v24, v23, v20
	v_sub_f32_e32 v26, v30, v26
	v_sub_f32_e32 v27, v24, v23
	v_add_f32_e32 v21, v21, v26
	v_sub_f32_e32 v26, v24, v27
	v_sub_f32_e32 v20, v20, v27
	v_sub_f32_e32 v23, v23, v26
	v_add_f32_e32 v21, v24, v21
	v_add_f32_e32 v20, v20, v23
	v_add_f32_e32 v23, v25, v21
	v_sub_f32_e32 v24, v23, v25
	v_sub_f32_e32 v21, v21, v24
	v_add_f32_e32 v20, v20, v21
	v_add_f32_e32 v20, v23, v20
	v_cmp_neq_f32_e64 s[0:1], s23, v22
	s_nop 1
	v_cndmask_b32_e64 v20, v7, v20, s[0:1]
	v_cmp_ngt_f32_e64 s[0:1], -1.0, v22
	s_nop 1
	v_cndmask_b32_e64 v20, v8, v20, s[0:1]
	v_cmp_neq_f32_e64 s[0:1], -1.0, v22
	s_nop 1
	v_cndmask_b32_e64 v20, v17, v20, s[0:1]
	v_cmp_lt_f32_e64 s[0:1], |v22|, s33
	s_nop 1
	v_cndmask_b32_e64 v20, v20, v22, s[0:1]
	v_sub_f32_e32 v19, v19, v20
	v_mul_f32_e32 v20, 0x3fb8aa3b, v19
	ds_bpermute_b32 v21, v10, v20
	s_or_b32 s0, s22, 6
	s_ashr_i32 s1, s0, 31
	s_lshl_b64 s[28:29], s[0:1], 14
	v_lshl_or_b32 v22, v12, 2, s28
	s_waitcnt lgkmcnt(0)
	v_fmac_f32_e32 v21, 0x3fb8aa3b, v19
	v_cndmask_b32_e64 v19, v21, v20, s[2:3]
	ds_bpermute_b32 v20, v11, v19
	v_mov_b32_e32 v23, s29
	v_lshl_add_u64 v[24:25], s[20:21], 0, v[22:23]
	v_lshl_add_u64 v[22:23], s[26:27], 0, v[22:23]
	s_waitcnt lgkmcnt(0)
	v_add_f32_e32 v20, v19, v20
	v_cndmask_b32_e64 v19, v20, v19, s[8:9]
	ds_bpermute_b32 v20, v13, v19
	s_waitcnt lgkmcnt(0)
	v_add_f32_e32 v20, v19, v20
	v_cndmask_b32_e64 v19, v20, v19, s[10:11]
	ds_bpermute_b32 v20, v14, v19
	s_waitcnt lgkmcnt(0)
	v_add_f32_e32 v20, v19, v20
	v_cndmask_b32_e64 v20, v20, v19, s[6:7]
	ds_bpermute_b32 v21, v15, v20
	v_mov_b32_e32 v19, 0x3f2aaada
	s_waitcnt lgkmcnt(0)
	v_add_f32_e32 v21, v20, v21
	v_cndmask_b32_e64 v21, v21, v20, s[12:13]
	ds_bpermute_b32 v20, v16, v21
	s_waitcnt lgkmcnt(0)
	v_add_f32_e32 v20, v21, v20
	v_cndmask_b32_e64 v21, v20, v21, s[4:5]
	global_store_dword v[24:25], v21, off
	v_xor_b32_e32 v21, 0x80000000, v21
	global_store_dword v[22:23], v21, off
	s_and_saveexec_b64 s[28:29], vcc
	s_cbranch_execz .LBB0_467
	s_lshl_b32 s0, s0, 6
	s_or_b32 s0, s0, s15
	s_ashr_i32 s1, s0, 31
	s_lshl_b64 s[0:1], s[0:1], 2
	s_add_u32 s0, s30, s0
	s_addc_u32 s1, s31, s1
	global_store_dword v18, v20, s[0:1]
; __global__ void __launch_bounds__(512, 2) fwd_kernel(Args a) {
;     ...
;             for (int hh = 0; hh < 16; ++hh) { const float z = fz[hh] + bfp[hh]; float incl = (fminf(z, 0.f) - log1pf(__expf(-fabsf(z)))) * LOG2E;
; #pragma unroll
;                 for (int o = 1; o < 64; o <<= 1) { const float t = __shfl_up(incl, o); if (lane >= o) incl += t; }
;                 cum[(size_t)(b * 16 + hh) * SEQ + ch * 64 + lane] = incl; ((float*)(ws + WS_NCUM))[(size_t)(b * 16 + hh) * SEQ + ch * 64 + lane] = -incl;
;                 if (lane == 63) totp[(b * 16 + hh) * 64 + ch] = incl; }
.LBB0_467:
	s_or_b64 exec, exec, s[28:29]
	v_mov_b32_e32 v18, v47
	v_and_b32_e32 v9, 0xffff0000, v9
	v_add_f32_e32 v9, v18, v9
	v_mul_f32_e64 v18, |v9|, s36
	v_exp_f32_e32 v18, v18
	v_min_f32_e32 v9, 0, v9
	v_add_f32_e32 v22, 1.0, v18
	v_add_f32_e32 v23, -1.0, v22
	v_frexp_mant_f32_e32 v24, v22
	v_cvt_f64_f32_e32 v[20:21], v22
	v_sub_f32_e32 v25, v23, v22
	v_frexp_exp_i32_f64_e32 v20, v[20:21]
	v_cmp_gt_f32_e64 s[0:1], s35, v24
	v_sub_f32_e32 v23, v18, v23
	v_add_f32_e32 v21, 1.0, v25
	v_subbrev_co_u32_e64 v20, s[0:1], 0, v20, s[0:1]
	v_add_f32_e32 v21, v23, v21
	v_sub_u32_e32 v23, 0, v20
	v_cvt_f32_i32_e32 v20, v20
	v_ldexp_f32 v22, v22, v23
	v_ldexp_f32 v21, v21, v23
	v_add_f32_e32 v23, -1.0, v22
	v_add_f32_e32 v24, 1.0, v22
	v_add_f32_e32 v25, 1.0, v23
	v_add_f32_e32 v26, -1.0, v24
	v_sub_f32_e32 v25, v22, v25
	v_sub_f32_e32 v22, v22, v26
	v_mul_f32_e32 v26, 0x3f317218, v20
	v_add_f32_e32 v25, v21, v25
	v_add_f32_e32 v21, v21, v22
	v_fma_f32 v22, v20, s34, -v26
	v_add_f32_e32 v27, v23, v25
	v_add_f32_e32 v28, v24, v21
	v_fmac_f32_e32 v22, 0xb102e308, v20
	v_sub_f32_e32 v20, v27, v23
	v_sub_f32_e32 v23, v28, v24
	v_rcp_f32_e32 v24, v28
	v_add_f32_e32 v29, v26, v22
	v_sub_f32_e32 v21, v21, v23
	v_sub_f32_e32 v23, v29, v26
	v_sub_f32_e32 v22, v22, v23
	v_mul_f32_e32 v23, v27, v24
	v_sub_f32_e32 v20, v25, v20
	v_mul_f32_e32 v25, v28, v23
	v_fma_f32 v26, v23, v28, -v25
	v_fmac_f32_e32 v26, v23, v21
	v_add_f32_e32 v30, v25, v26
	v_sub_f32_e32 v31, v27, v30
	v_sub_f32_e32 v25, v30, v25
	v_sub_f32_e32 v27, v27, v31
	v_sub_f32_e32 v25, v25, v26
	v_sub_f32_e32 v26, v27, v30
	v_add_f32_e32 v20, v20, v26
	v_add_f32_e32 v20, v25, v20
	v_add_f32_e32 v25, v31, v20
	v_mul_f32_e32 v26, v24, v25
	v_sub_f32_e32 v27, v31, v25
	v_mul_f32_e32 v30, v28, v26
	v_add_f32_e32 v20, v20, v27
	v_add_f32_e32 v27, v23, v26
	v_fma_f32 v28, v26, v28, -v30
	v_sub_f32_e32 v23, v27, v23
	v_fmac_f32_e32 v28, v26, v21
	v_sub_f32_e32 v21, v26, v23
	v_add_f32_e32 v23, v30, v28
	v_sub_f32_e32 v26, v23, v30
	v_sub_f32_e32 v30, v25, v23
	v_sub_f32_e32 v25, v25, v30
	v_sub_f32_e32 v23, v25, v23
	v_sub_f32_e32 v26, v26, v28
	v_add_f32_e32 v20, v20, v23
	v_add_f32_e32 v20, v26, v20
	v_add_f32_e32 v20, v30, v20
	v_mul_f32_e32 v20, v24, v20
	v_add_f32_e32 v20, v21, v20
	v_add_f32_e32 v21, v27, v20
	v_mul_f32_e32 v23, v21, v21
	v_fmac_f32_e32 v6, 0x3e9b6dac, v23
	v_sub_f32_e32 v24, v21, v27
	v_ldexp_f32 v25, v21, 1
	v_mul_f32_e32 v21, v21, v23
	v_fmac_f32_e32 v19, v23, v6
	v_sub_f32_e32 v20, v20, v24
	v_mul_f32_e32 v19, v21, v19
	v_ldexp_f32 v6, v20, 1
	v_add_f32_e32 v20, v25, v19
	v_sub_f32_e32 v21, v20, v25
	v_sub_f32_e32 v19, v19, v21
	v_add_f32_e32 v6, v6, v19
	v_add_f32_e32 v19, v20, v6
	v_sub_f32_e32 v20, v19, v20
	v_add_f32_e32 v21, v29, v19
	v_sub_f32_e32 v6, v6, v20
	v_sub_f32_e32 v20, v21, v29
	v_sub_f32_e32 v23, v21, v20
	v_sub_f32_e32 v19, v19, v20
	v_sub_f32_e32 v23, v29, v23
	v_add_f32_e32 v20, v22, v6
	v_add_f32_e32 v19, v19, v23
	v_sub_f32_e32 v24, v20, v22
	v_add_f32_e32 v19, v20, v19
	v_sub_f32_e32 v23, v20, v24
	v_add_f32_e32 v20, v21, v19
	v_sub_f32_e32 v6, v6, v24
	v_sub_f32_e32 v22, v22, v23
	v_sub_f32_e32 v21, v20, v21
	v_add_f32_e32 v6, v6, v22
	v_sub_f32_e32 v19, v19, v21
	v_add_f32_e32 v6, v6, v19
	v_add_f32_e32 v6, v20, v6
	v_cmp_neq_f32_e64 s[0:1], s23, v18
	s_nop 1
	v_cndmask_b32_e64 v6, v7, v6, s[0:1]
	v_cmp_ngt_f32_e64 s[0:1], -1.0, v18
	s_nop 1
	v_cndmask_b32_e64 v6, v8, v6, s[0:1]
	v_cmp_neq_f32_e64 s[0:1], -1.0, v18
	s_nop 1
	v_cndmask_b32_e64 v6, v17, v6, s[0:1]
	v_cmp_lt_f32_e64 s[0:1], |v18|, s33
	s_nop 1
	v_cndmask_b32_e64 v6, v6, v18, s[0:1]
	v_sub_f32_e32 v6, v9, v6
	v_mul_f32_e32 v7, 0x3fb8aa3b, v6
	ds_bpermute_b32 v8, v10, v7
	s_or_b32 s0, s22, 7
	s_ashr_i32 s1, s0, 31
	s_lshl_b64 s[28:29], s[0:1], 14
	v_mov_b32_e32 v9, s29
	s_waitcnt lgkmcnt(0)
	v_fmac_f32_e32 v8, 0x3fb8aa3b, v6
	v_cndmask_b32_e64 v6, v8, v7, s[2:3]
	ds_bpermute_b32 v7, v11, v6
	v_lshl_or_b32 v8, v12, 2, s28
	v_lshl_add_u64 v[18:19], s[20:21], 0, v[8:9]
	v_lshl_add_u64 v[8:9], s[26:27], 0, v[8:9]
	s_waitcnt lgkmcnt(0)
	v_add_f32_e32 v7, v6, v7
	v_cndmask_b32_e64 v6, v7, v6, s[8:9]
	ds_bpermute_b32 v7, v13, v6
	s_waitcnt lgkmcnt(0)
	v_add_f32_e32 v7, v6, v7
	v_cndmask_b32_e64 v6, v7, v6, s[10:11]
	ds_bpermute_b32 v7, v14, v6
	s_waitcnt lgkmcnt(0)
	v_add_f32_e32 v7, v6, v7
	v_cndmask_b32_e64 v6, v7, v6, s[6:7]
	ds_bpermute_b32 v7, v15, v6
	s_waitcnt lgkmcnt(0)
	v_add_f32_e32 v7, v6, v7
	v_cndmask_b32_e64 v7, v7, v6, s[12:13]
	ds_bpermute_b32 v6, v16, v7
	s_waitcnt lgkmcnt(0)
	v_add_f32_e32 v6, v7, v6
	v_cndmask_b32_e64 v7, v6, v7, s[4:5]
	global_store_dword v[18:19], v7, off
	v_xor_b32_e32 v7, 0x80000000, v7
	global_store_dword v[8:9], v7, off
	s_and_saveexec_b64 s[28:29], vcc
	s_cbranch_execz .LBB0_469
	s_lshl_b32 s0, s0, 6
	s_or_b32 s0, s0, s15
	s_ashr_i32 s1, s0, 31
	s_lshl_b64 s[0:1], s[0:1], 2
	s_add_u32 s0, s30, s0
	s_addc_u32 s1, s31, s1
	v_mov_b32_e32 v7, 0
	global_store_dword v7, v6, s[0:1]
; __global__ void __launch_bounds__(512, 2) fwd_kernel(Args a) {
;     ...
;             for (int hh = 0; hh < 16; ++hh) { const float z = fz[hh] + bfp[hh]; float incl = (fminf(z, 0.f) - log1pf(__expf(-fabsf(z)))) * LOG2E;
; #pragma unroll
;                 for (int o = 1; o < 64; o <<= 1) { const float t = __shfl_up(incl, o); if (lane >= o) incl += t; }
;                 cum[(size_t)(b * 16 + hh) * SEQ + ch * 64 + lane] = incl; ((float*)(ws + WS_NCUM))[(size_t)(b * 16 + hh) * SEQ + ch * 64 + lane] = -incl;
;                 if (lane == 63) totp[(b * 16 + hh) * 64 + ch] = incl; }
.LBB0_469:
	s_or_b64 exec, exec, s[28:29]
	v_mov_b32_e32 v17, 0
	v_mov_b32_e32 v9, v48
	v_lshlrev_b32_e32 v18, 16, v2
	v_mov_b32_e32 v6, 0x3ecc95a3
	v_mov_b32_e32 v7, 0x7f800000
	v_mov_b32_e32 v8, 0x7fc00000
	v_add_f32_e32 v18, v9, v18
	v_mul_f32_e64 v9, |v18|, s36
	v_exp_f32_e32 v20, v9
	v_min_f32_e32 v21, 0, v18
	v_mov_b32_e32 v9, 0xff800000
	v_add_f32_e32 v22, 1.0, v20
	v_add_f32_e32 v23, -1.0, v22
	v_frexp_mant_f32_e32 v24, v22
	v_cvt_f64_f32_e32 v[18:19], v22
	v_sub_f32_e32 v25, v23, v22
	v_frexp_exp_i32_f64_e32 v18, v[18:19]
	v_cmp_gt_f32_e64 s[0:1], s35, v24
	v_sub_f32_e32 v23, v20, v23
	v_add_f32_e32 v19, 1.0, v25
	v_subbrev_co_u32_e64 v18, s[0:1], 0, v18, s[0:1]
	v_add_f32_e32 v19, v23, v19
	v_sub_u32_e32 v23, 0, v18
	v_cvt_f32_i32_e32 v18, v18
	v_ldexp_f32 v22, v22, v23
	v_ldexp_f32 v19, v19, v23
	v_add_f32_e32 v23, -1.0, v22
	v_add_f32_e32 v24, 1.0, v22
	v_add_f32_e32 v25, 1.0, v23
	v_add_f32_e32 v26, -1.0, v24
	v_sub_f32_e32 v25, v22, v25
	v_sub_f32_e32 v22, v22, v26
	v_mul_f32_e32 v26, 0x3f317218, v18
	v_add_f32_e32 v25, v19, v25
	v_add_f32_e32 v19, v19, v22
	v_fma_f32 v22, v18, s34, -v26
	v_add_f32_e32 v27, v23, v25
	v_add_f32_e32 v28, v24, v19
	v_fmac_f32_e32 v22, 0xb102e308, v18
	v_sub_f32_e32 v18, v27, v23
	v_sub_f32_e32 v23, v28, v24
	v_rcp_f32_e32 v24, v28
	v_add_f32_e32 v29, v26, v22
	v_sub_f32_e32 v19, v19, v23
	v_sub_f32_e32 v23, v29, v26
	v_sub_f32_e32 v22, v22, v23
	v_mul_f32_e32 v23, v27, v24
	v_sub_f32_e32 v18, v25, v18
	v_mul_f32_e32 v25, v28, v23
	v_fma_f32 v26, v23, v28, -v25
	v_fmac_f32_e32 v26, v23, v19
	v_add_f32_e32 v30, v25, v26
	v_sub_f32_e32 v31, v27, v30
	v_sub_f32_e32 v25, v30, v25
	v_sub_f32_e32 v27, v27, v31
	v_sub_f32_e32 v25, v25, v26
	v_sub_f32_e32 v26, v27, v30
	v_add_f32_e32 v18, v18, v26
	v_add_f32_e32 v18, v25, v18
	v_add_f32_e32 v25, v31, v18
	v_mul_f32_e32 v26, v24, v25
	v_sub_f32_e32 v27, v31, v25
	v_mul_f32_e32 v30, v28, v26
	v_add_f32_e32 v18, v18, v27
	v_add_f32_e32 v27, v23, v26
	v_fma_f32 v28, v26, v28, -v30
	v_sub_f32_e32 v23, v27, v23
	v_fmac_f32_e32 v28, v26, v19
	v_sub_f32_e32 v19, v26, v23
	v_add_f32_e32 v23, v30, v28
	v_sub_f32_e32 v26, v23, v30
	v_sub_f32_e32 v30, v25, v23
	v_sub_f32_e32 v25, v25, v30
	v_sub_f32_e32 v23, v25, v23
	v_sub_f32_e32 v26, v26, v28
	v_add_f32_e32 v18, v18, v23
	v_add_f32_e32 v18, v26, v18
	v_add_f32_e32 v18, v30, v18
	v_mul_f32_e32 v18, v24, v18
	v_add_f32_e32 v18, v19, v18
	v_add_f32_e32 v19, v27, v18
	v_mul_f32_e32 v23, v19, v19
	v_fmamk_f32 v26, v23, 0x3e9b6dac, v6
	v_sub_f32_e32 v24, v19, v27
	v_ldexp_f32 v25, v19, 1
	v_mul_f32_e32 v19, v19, v23
	v_fmaak_f32 v23, v23, v26, 0x3f2aaada
	v_mul_f32_e32 v19, v19, v23
	v_add_f32_e32 v23, v25, v19
	v_sub_f32_e32 v18, v18, v24
	v_sub_f32_e32 v24, v23, v25
	v_ldexp_f32 v18, v18, 1
	v_sub_f32_e32 v19, v19, v24
	v_add_f32_e32 v18, v18, v19
	v_add_f32_e32 v19, v23, v18
	v_sub_f32_e32 v23, v19, v23
	v_add_f32_e32 v24, v29, v19
	v_sub_f32_e32 v18, v18, v23
	v_sub_f32_e32 v23, v24, v29
	v_sub_f32_e32 v25, v24, v23
	v_sub_f32_e32 v19, v19, v23
	v_add_f32_e32 v23, v22, v18
	v_sub_f32_e32 v25, v29, v25
	v_sub_f32_e32 v26, v23, v22
	v_add_f32_e32 v19, v19, v25
	v_sub_f32_e32 v25, v23, v26
	v_sub_f32_e32 v18, v18, v26
	v_sub_f32_e32 v22, v22, v25
	v_add_f32_e32 v19, v23, v19
	v_add_f32_e32 v18, v18, v22
	v_add_f32_e32 v22, v24, v19
	v_sub_f32_e32 v23, v22, v24
	v_sub_f32_e32 v19, v19, v23
	v_add_f32_e32 v18, v18, v19
	v_add_f32_e32 v18, v22, v18
	v_cmp_neq_f32_e64 s[0:1], s23, v20
	s_nop 1
	v_cndmask_b32_e64 v18, v7, v18, s[0:1]
	v_cmp_ngt_f32_e64 s[0:1], -1.0, v20
	s_nop 1
	v_cndmask_b32_e64 v18, v8, v18, s[0:1]
	v_cmp_neq_f32_e64 s[0:1], -1.0, v20
	s_nop 1
	v_cndmask_b32_e64 v18, v9, v18, s[0:1]
	v_cmp_lt_f32_e64 s[0:1], |v20|, s33
	s_nop 1
	v_cndmask_b32_e64 v18, v18, v20, s[0:1]
	v_sub_f32_e32 v18, v21, v18
	v_mul_f32_e32 v19, 0x3fb8aa3b, v18
	ds_bpermute_b32 v20, v10, v19
	s_or_b32 s0, s22, 8
	s_ashr_i32 s1, s0, 31
	s_lshl_b64 s[28:29], s[0:1], 14
	v_mov_b32_e32 v21, s29
	s_waitcnt lgkmcnt(0)
	v_fmac_f32_e32 v20, 0x3fb8aa3b, v18
	v_cndmask_b32_e64 v18, v20, v19, s[2:3]
	ds_bpermute_b32 v19, v11, v18
	s_waitcnt lgkmcnt(0)
	v_add_f32_e32 v19, v18, v19
	v_cndmask_b32_e64 v18, v19, v18, s[8:9]
	ds_bpermute_b32 v19, v13, v18
	s_waitcnt lgkmcnt(0)
	v_add_f32_e32 v19, v18, v19
	v_cndmask_b32_e64 v18, v19, v18, s[10:11]
	ds_bpermute_b32 v19, v14, v18
	s_waitcnt lgkmcnt(0)
	v_add_f32_e32 v19, v18, v19
	v_cndmask_b32_e64 v19, v19, v18, s[6:7]
	ds_bpermute_b32 v20, v15, v19
	v_mov_b32_e32 v18, 0x3f2aaada
	s_waitcnt lgkmcnt(0)
	v_add_f32_e32 v20, v19, v20
	v_cndmask_b32_e64 v24, v20, v19, s[12:13]
	ds_bpermute_b32 v19, v16, v24
	v_lshl_or_b32 v20, v12, 2, s28
	v_lshl_add_u64 v[22:23], s[20:21], 0, v[20:21]
	v_lshl_add_u64 v[20:21], s[26:27], 0, v[20:21]
	s_waitcnt lgkmcnt(0)
	v_add_f32_e32 v19, v24, v19
	v_cndmask_b32_e64 v24, v19, v24, s[4:5]
	global_store_dword v[22:23], v24, off
	v_xor_b32_e32 v22, 0x80000000, v24
	global_store_dword v[20:21], v22, off
	s_and_saveexec_b64 s[28:29], vcc
	s_cbranch_execz .LBB0_471
	s_lshl_b32 s0, s0, 6
	s_or_b32 s0, s0, s15
	s_ashr_i32 s1, s0, 31
	s_lshl_b64 s[0:1], s[0:1], 2
	s_add_u32 s0, s30, s0
	s_addc_u32 s1, s31, s1
	global_store_dword v17, v19, s[0:1]
; __global__ void __launch_bounds__(512, 2) fwd_kernel(Args a) {
;     ...
;             for (int hh = 0; hh < 16; ++hh) { const float z = fz[hh] + bfp[hh]; float incl = (fminf(z, 0.f) - log1pf(__expf(-fabsf(z)))) * LOG2E;
; #pragma unroll
;                 for (int o = 1; o < 64; o <<= 1) { const float t = __shfl_up(incl, o); if (lane >= o) incl += t; }
;                 cum[(size_t)(b * 16 + hh) * SEQ + ch * 64 + lane] = incl; ((float*)(ws + WS_NCUM))[(size_t)(b * 16 + hh) * SEQ + ch * 64 + lane] = -incl;
;                 if (lane == 63) totp[(b * 16 + hh) * 64 + ch] = incl; }
.LBB0_471:
	s_or_b64 exec, exec, s[28:29]
	v_mov_b32_e32 v17, v49
	v_and_b32_e32 v2, 0xffff0000, v2
	v_add_f32_e32 v2, v17, v2
	v_mul_f32_e64 v17, |v2|, s36
	v_exp_f32_e32 v17, v17
	v_min_f32_e32 v2, 0, v2
	v_add_f32_e32 v19, 1.0, v17
	v_add_f32_e32 v22, -1.0, v19
	v_frexp_mant_f32_e32 v23, v19
	v_cvt_f64_f32_e32 v[20:21], v19
	v_sub_f32_e32 v24, v22, v19
	v_frexp_exp_i32_f64_e32 v20, v[20:21]
	v_cmp_gt_f32_e64 s[0:1], s35, v23
	v_sub_f32_e32 v22, v17, v22
	v_add_f32_e32 v21, 1.0, v24
	v_subbrev_co_u32_e64 v20, s[0:1], 0, v20, s[0:1]
	v_add_f32_e32 v21, v22, v21
	v_sub_u32_e32 v22, 0, v20
	v_cvt_f32_i32_e32 v20, v20
	v_ldexp_f32 v19, v19, v22
	v_ldexp_f32 v21, v21, v22
	v_add_f32_e32 v22, -1.0, v19
	v_add_f32_e32 v23, 1.0, v19
	v_add_f32_e32 v24, 1.0, v22
	v_add_f32_e32 v25, -1.0, v23
	v_sub_f32_e32 v24, v19, v24
	v_sub_f32_e32 v19, v19, v25
	v_mul_f32_e32 v25, 0x3f317218, v20
	v_add_f32_e32 v24, v21, v24
	v_add_f32_e32 v19, v21, v19
	v_fma_f32 v21, v20, s34, -v25
	v_add_f32_e32 v26, v22, v24
	v_add_f32_e32 v27, v23, v19
	v_fmac_f32_e32 v21, 0xb102e308, v20
	v_sub_f32_e32 v20, v26, v22
	v_sub_f32_e32 v22, v27, v23
	v_rcp_f32_e32 v23, v27
	v_add_f32_e32 v28, v25, v21
	v_sub_f32_e32 v19, v19, v22
	v_sub_f32_e32 v22, v28, v25
	v_sub_f32_e32 v21, v21, v22
	v_mul_f32_e32 v22, v26, v23
	v_sub_f32_e32 v20, v24, v20
	v_mul_f32_e32 v24, v27, v22
	v_fma_f32 v25, v22, v27, -v24
	v_fmac_f32_e32 v25, v22, v19
	v_add_f32_e32 v29, v24, v25
	v_sub_f32_e32 v30, v26, v29
	v_sub_f32_e32 v24, v29, v24
	v_sub_f32_e32 v26, v26, v30
	v_sub_f32_e32 v24, v24, v25
	v_sub_f32_e32 v25, v26, v29
	v_add_f32_e32 v20, v20, v25
	v_add_f32_e32 v20, v24, v20
	v_add_f32_e32 v24, v30, v20
	v_mul_f32_e32 v25, v23, v24
	v_sub_f32_e32 v26, v30, v24
	v_mul_f32_e32 v29, v27, v25
	v_add_f32_e32 v20, v20, v26
	v_add_f32_e32 v26, v22, v25
	v_fma_f32 v27, v25, v27, -v29
	v_sub_f32_e32 v22, v26, v22
	v_fmac_f32_e32 v27, v25, v19
	v_sub_f32_e32 v19, v25, v22
	v_add_f32_e32 v22, v29, v27
	v_sub_f32_e32 v25, v22, v29
	v_sub_f32_e32 v29, v24, v22
	v_sub_f32_e32 v24, v24, v29
	v_sub_f32_e32 v22, v24, v22
	v_sub_f32_e32 v25, v25, v27
	v_add_f32_e32 v20, v20, v22
	v_add_f32_e32 v20, v25, v20
	v_add_f32_e32 v20, v29, v20
	v_mul_f32_e32 v20, v23, v20
	v_add_f32_e32 v19, v19, v20
	v_add_f32_e32 v20, v26, v19
	v_mul_f32_e32 v22, v20, v20
	v_fmac_f32_e32 v6, 0x3e9b6dac, v22
	v_sub_f32_e32 v23, v20, v26
	v_ldexp_f32 v24, v20, 1
	v_mul_f32_e32 v20, v20, v22
	v_fmac_f32_e32 v18, v22, v6
	v_sub_f32_e32 v19, v19, v23
	v_mul_f32_e32 v18, v20, v18
	v_ldexp_f32 v6, v19, 1
	v_add_f32_e32 v19, v24, v18
	v_sub_f32_e32 v20, v19, v24
	v_sub_f32_e32 v18, v18, v20
	v_add_f32_e32 v6, v6, v18
	v_add_f32_e32 v18, v19, v6
	v_sub_f32_e32 v19, v18, v19
	v_add_f32_e32 v20, v28, v18
	v_sub_f32_e32 v6, v6, v19
	v_sub_f32_e32 v19, v20, v28
	v_sub_f32_e32 v22, v20, v19
	v_sub_f32_e32 v18, v18, v19
	v_sub_f32_e32 v22, v28, v22
	v_add_f32_e32 v19, v21, v6
	v_add_f32_e32 v18, v18, v22
	v_sub_f32_e32 v23, v19, v21
	v_add_f32_e32 v18, v19, v18
	v_sub_f32_e32 v22, v19, v23
	v_add_f32_e32 v19, v20, v18
	v_sub_f32_e32 v6, v6, v23
	v_sub_f32_e32 v21, v21, v22
	v_sub_f32_e32 v20, v19, v20
	v_add_f32_e32 v6, v6, v21
	v_sub_f32_e32 v18, v18, v20
	v_add_f32_e32 v6, v6, v18
	v_add_f32_e32 v6, v19, v6
	v_cmp_neq_f32_e64 s[0:1], s23, v17
	s_nop 1
	v_cndmask_b32_e64 v6, v7, v6, s[0:1]
	v_cmp_ngt_f32_e64 s[0:1], -1.0, v17
	s_nop 1
	v_cndmask_b32_e64 v6, v8, v6, s[0:1]
	v_cmp_neq_f32_e64 s[0:1], -1.0, v17
	s_nop 1
	v_cndmask_b32_e64 v6, v9, v6, s[0:1]
	v_cmp_lt_f32_e64 s[0:1], |v17|, s33
	s_nop 1
	v_cndmask_b32_e64 v6, v6, v17, s[0:1]
	v_sub_f32_e32 v2, v2, v6
	v_mul_f32_e32 v6, 0x3fb8aa3b, v2
	ds_bpermute_b32 v7, v10, v6
	s_or_b32 s0, s22, 9
	s_ashr_i32 s1, s0, 31
	s_lshl_b64 s[28:29], s[0:1], 14
	s_waitcnt lgkmcnt(0)
	v_fmac_f32_e32 v7, 0x3fb8aa3b, v2
	v_cndmask_b32_e64 v2, v7, v6, s[2:3]
	ds_bpermute_b32 v6, v11, v2
	v_mov_b32_e32 v7, s29
	s_waitcnt lgkmcnt(0)
	v_add_f32_e32 v6, v2, v6
	v_cndmask_b32_e64 v2, v6, v2, s[8:9]
	ds_bpermute_b32 v6, v13, v2
	s_waitcnt lgkmcnt(0)
	v_add_f32_e32 v6, v2, v6
	v_cndmask_b32_e64 v2, v6, v2, s[10:11]
	ds_bpermute_b32 v6, v14, v2
	s_waitcnt lgkmcnt(0)
	v_add_f32_e32 v6, v2, v6
	v_cndmask_b32_e64 v2, v6, v2, s[6:7]
	ds_bpermute_b32 v6, v15, v2
	s_waitcnt lgkmcnt(0)
	v_add_f32_e32 v6, v2, v6
	v_cndmask_b32_e64 v17, v6, v2, s[12:13]
	ds_bpermute_b32 v2, v16, v17
	v_lshl_or_b32 v6, v12, 2, s28
	v_lshl_add_u64 v[8:9], s[20:21], 0, v[6:7]
	v_lshl_add_u64 v[6:7], s[26:27], 0, v[6:7]
	s_waitcnt lgkmcnt(0)
	v_add_f32_e32 v2, v17, v2
	v_cndmask_b32_e64 v17, v2, v17, s[4:5]
	global_store_dword v[8:9], v17, off
	v_xor_b32_e32 v8, 0x80000000, v17
	global_store_dword v[6:7], v8, off
	s_and_saveexec_b64 s[28:29], vcc
	s_cbranch_execz .LBB0_473
	s_lshl_b32 s0, s0, 6
	s_or_b32 s0, s0, s15
	s_ashr_i32 s1, s0, 31
	s_lshl_b64 s[0:1], s[0:1], 2
	s_add_u32 s0, s30, s0
	s_addc_u32 s1, s31, s1
	v_mov_b32_e32 v6, 0
	global_store_dword v6, v2, s[0:1]
; __global__ void __launch_bounds__(512, 2) fwd_kernel(Args a) {
;     ...
;             for (int hh = 0; hh < 16; ++hh) { const float z = fz[hh] + bfp[hh]; float incl = (fminf(z, 0.f) - log1pf(__expf(-fabsf(z)))) * LOG2E;
; #pragma unroll
;                 for (int o = 1; o < 64; o <<= 1) { const float t = __shfl_up(incl, o); if (lane >= o) incl += t; }
;                 cum[(size_t)(b * 16 + hh) * SEQ + ch * 64 + lane] = incl; ((float*)(ws + WS_NCUM))[(size_t)(b * 16 + hh) * SEQ + ch * 64 + lane] = -incl;
;                 if (lane == 63) totp[(b * 16 + hh) * 64 + ch] = incl; }
.LBB0_473:
	s_or_b64 exec, exec, s[28:29]
	v_mov_b32_e32 v9, 0
	v_mov_b32_e32 v8, v50
	v_lshlrev_b32_e32 v17, 16, v3
	v_mov_b32_e32 v2, 0x3ecc95a3
	v_mov_b32_e32 v6, 0x7f800000
	v_mov_b32_e32 v7, 0x7fc00000
	v_add_f32_e32 v17, v8, v17
	v_mul_f32_e64 v8, |v17|, s36
	v_exp_f32_e32 v20, v8
	v_mov_b32_e32 v8, 0xff800000
	v_min_f32_e32 v17, 0, v17
	v_add_f32_e32 v21, 1.0, v20
	v_add_f32_e32 v22, -1.0, v21
	v_frexp_mant_f32_e32 v23, v21
	v_cvt_f64_f32_e32 v[18:19], v21
	v_sub_f32_e32 v24, v22, v21
	v_frexp_exp_i32_f64_e32 v18, v[18:19]
	v_cmp_gt_f32_e64 s[0:1], s35, v23
	v_sub_f32_e32 v22, v20, v22
	v_add_f32_e32 v19, 1.0, v24
	v_subbrev_co_u32_e64 v18, s[0:1], 0, v18, s[0:1]
	v_add_f32_e32 v19, v22, v19
	v_sub_u32_e32 v22, 0, v18
	v_cvt_f32_i32_e32 v18, v18
	v_ldexp_f32 v21, v21, v22
	v_ldexp_f32 v19, v19, v22
	v_add_f32_e32 v22, -1.0, v21
	v_add_f32_e32 v23, 1.0, v21
	v_add_f32_e32 v24, 1.0, v22
	v_add_f32_e32 v25, -1.0, v23
	v_sub_f32_e32 v24, v21, v24
	v_sub_f32_e32 v21, v21, v25
	v_mul_f32_e32 v25, 0x3f317218, v18
	v_add_f32_e32 v24, v19, v24
	v_add_f32_e32 v19, v19, v21
	v_fma_f32 v21, v18, s34, -v25
	v_add_f32_e32 v26, v22, v24
	v_add_f32_e32 v27, v23, v19
	v_fmac_f32_e32 v21, 0xb102e308, v18
	v_sub_f32_e32 v18, v26, v22
	v_sub_f32_e32 v22, v27, v23
	v_rcp_f32_e32 v23, v27
	v_add_f32_e32 v28, v25, v21
	v_sub_f32_e32 v19, v19, v22
	v_sub_f32_e32 v22, v28, v25
	v_sub_f32_e32 v21, v21, v22
	v_mul_f32_e32 v22, v26, v23
	v_sub_f32_e32 v18, v24, v18
	v_mul_f32_e32 v24, v27, v22
	v_fma_f32 v25, v22, v27, -v24
	v_fmac_f32_e32 v25, v22, v19
	v_add_f32_e32 v29, v24, v25
	v_sub_f32_e32 v30, v26, v29
	v_sub_f32_e32 v24, v29, v24
	v_sub_f32_e32 v26, v26, v30
	v_sub_f32_e32 v24, v24, v25
	v_sub_f32_e32 v25, v26, v29
	v_add_f32_e32 v18, v18, v25
	v_add_f32_e32 v18, v24, v18
	v_add_f32_e32 v24, v30, v18
	v_mul_f32_e32 v25, v23, v24
	v_sub_f32_e32 v26, v30, v24
	v_mul_f32_e32 v29, v27, v25
	v_add_f32_e32 v18, v18, v26
	v_add_f32_e32 v26, v22, v25
	v_fma_f32 v27, v25, v27, -v29
	v_sub_f32_e32 v22, v26, v22
	v_fmac_f32_e32 v27, v25, v19
	v_sub_f32_e32 v19, v25, v22
	v_add_f32_e32 v22, v29, v27
	v_sub_f32_e32 v25, v22, v29
	v_sub_f32_e32 v29, v24, v22
	v_sub_f32_e32 v24, v24, v29
	v_sub_f32_e32 v22, v24, v22
	v_sub_f32_e32 v25, v25, v27
	v_add_f32_e32 v18, v18, v22
	v_add_f32_e32 v18, v25, v18
	v_add_f32_e32 v18, v29, v18
	v_mul_f32_e32 v18, v23, v18
	v_add_f32_e32 v18, v19, v18
	v_add_f32_e32 v19, v26, v18
	v_mul_f32_e32 v22, v19, v19
	v_fmamk_f32 v25, v22, 0x3e9b6dac, v2
	v_sub_f32_e32 v23, v19, v26
	v_ldexp_f32 v24, v19, 1
	v_mul_f32_e32 v19, v19, v22
	v_fmaak_f32 v22, v22, v25, 0x3f2aaada
	v_mul_f32_e32 v19, v19, v22
	v_add_f32_e32 v22, v24, v19
	v_sub_f32_e32 v18, v18, v23
	v_sub_f32_e32 v23, v22, v24
	v_ldexp_f32 v18, v18, 1
	v_sub_f32_e32 v19, v19, v23
	v_add_f32_e32 v18, v18, v19
	v_add_f32_e32 v19, v22, v18
	v_sub_f32_e32 v22, v19, v22
	v_add_f32_e32 v23, v28, v19
	v_sub_f32_e32 v18, v18, v22
	v_sub_f32_e32 v22, v23, v28
	v_sub_f32_e32 v24, v23, v22
	v_sub_f32_e32 v19, v19, v22
	v_add_f32_e32 v22, v21, v18
	v_sub_f32_e32 v24, v28, v24
	v_sub_f32_e32 v25, v22, v21
	v_add_f32_e32 v19, v19, v24
	v_sub_f32_e32 v24, v22, v25
	v_sub_f32_e32 v18, v18, v25
	v_sub_f32_e32 v21, v21, v24
	v_add_f32_e32 v19, v22, v19
	v_add_f32_e32 v18, v18, v21
	v_add_f32_e32 v21, v23, v19
	v_sub_f32_e32 v22, v21, v23
	v_sub_f32_e32 v19, v19, v22
	v_add_f32_e32 v18, v18, v19
	v_add_f32_e32 v18, v21, v18
	v_cmp_neq_f32_e64 s[0:1], s23, v20
	s_nop 1
	v_cndmask_b32_e64 v18, v6, v18, s[0:1]
	v_cmp_ngt_f32_e64 s[0:1], -1.0, v20
	s_nop 1
	v_cndmask_b32_e64 v18, v7, v18, s[0:1]
	v_cmp_neq_f32_e64 s[0:1], -1.0, v20
	s_nop 1
	v_cndmask_b32_e64 v18, v8, v18, s[0:1]
	v_cmp_lt_f32_e64 s[0:1], |v20|, s33
	s_nop 1
	v_cndmask_b32_e64 v18, v18, v20, s[0:1]
	v_sub_f32_e32 v17, v17, v18
	v_mul_f32_e32 v18, 0x3fb8aa3b, v17
	ds_bpermute_b32 v19, v10, v18
	s_or_b32 s0, s22, 10
	s_ashr_i32 s1, s0, 31
	s_lshl_b64 s[28:29], s[0:1], 14
	v_lshl_or_b32 v20, v12, 2, s28
	s_waitcnt lgkmcnt(0)
	v_fmac_f32_e32 v19, 0x3fb8aa3b, v17
	v_cndmask_b32_e64 v17, v19, v18, s[2:3]
	ds_bpermute_b32 v18, v11, v17
	v_mov_b32_e32 v21, s29
	v_lshl_add_u64 v[22:23], s[20:21], 0, v[20:21]
	v_lshl_add_u64 v[20:21], s[26:27], 0, v[20:21]
	s_waitcnt lgkmcnt(0)
	v_add_f32_e32 v18, v17, v18
	v_cndmask_b32_e64 v17, v18, v17, s[8:9]
	ds_bpermute_b32 v18, v13, v17
	s_waitcnt lgkmcnt(0)
	v_add_f32_e32 v18, v17, v18
	v_cndmask_b32_e64 v17, v18, v17, s[10:11]
	ds_bpermute_b32 v18, v14, v17
	s_waitcnt lgkmcnt(0)
	v_add_f32_e32 v18, v17, v18
	v_cndmask_b32_e64 v18, v18, v17, s[6:7]
	ds_bpermute_b32 v19, v15, v18
	v_mov_b32_e32 v17, 0x3f2aaada
	s_waitcnt lgkmcnt(0)
	v_add_f32_e32 v19, v18, v19
	v_cndmask_b32_e64 v19, v19, v18, s[12:13]
	ds_bpermute_b32 v18, v16, v19
	s_waitcnt lgkmcnt(0)
	v_add_f32_e32 v18, v19, v18
	v_cndmask_b32_e64 v19, v18, v19, s[4:5]
	global_store_dword v[22:23], v19, off
	v_xor_b32_e32 v19, 0x80000000, v19
	global_store_dword v[20:21], v19, off
	s_and_saveexec_b64 s[28:29], vcc
	s_cbranch_execz .LBB0_475
	s_lshl_b32 s0, s0, 6
	s_or_b32 s0, s0, s15
	s_ashr_i32 s1, s0, 31
	s_lshl_b64 s[0:1], s[0:1], 2
	s_add_u32 s0, s30, s0
	s_addc_u32 s1, s31, s1
	global_store_dword v9, v18, s[0:1]
; __global__ void __launch_bounds__(512, 2) fwd_kernel(Args a) {
;     ...
;             for (int hh = 0; hh < 16; ++hh) { const float z = fz[hh] + bfp[hh]; float incl = (fminf(z, 0.f) - log1pf(__expf(-fabsf(z)))) * LOG2E;
; #pragma unroll
;                 for (int o = 1; o < 64; o <<= 1) { const float t = __shfl_up(incl, o); if (lane >= o) incl += t; }
;                 cum[(size_t)(b * 16 + hh) * SEQ + ch * 64 + lane] = incl; ((float*)(ws + WS_NCUM))[(size_t)(b * 16 + hh) * SEQ + ch * 64 + lane] = -incl;
;                 if (lane == 63) totp[(b * 16 + hh) * 64 + ch] = incl; }
.LBB0_475:
	s_or_b64 exec, exec, s[28:29]
	v_mov_b32_e32 v9, v51
	v_and_b32_e32 v3, 0xffff0000, v3
	v_add_f32_e32 v3, v9, v3
	v_mul_f32_e64 v9, |v3|, s36
	v_exp_f32_e32 v9, v9
	v_min_f32_e32 v3, 0, v3
	v_add_f32_e32 v20, 1.0, v9
	v_add_f32_e32 v21, -1.0, v20
	v_frexp_mant_f32_e32 v22, v20
	v_cvt_f64_f32_e32 v[18:19], v20
	v_sub_f32_e32 v23, v21, v20
	v_frexp_exp_i32_f64_e32 v18, v[18:19]
	v_cmp_gt_f32_e64 s[0:1], s35, v22
	v_sub_f32_e32 v21, v9, v21
	v_add_f32_e32 v19, 1.0, v23
	v_subbrev_co_u32_e64 v18, s[0:1], 0, v18, s[0:1]
	v_add_f32_e32 v19, v21, v19
	v_sub_u32_e32 v21, 0, v18
	v_cvt_f32_i32_e32 v18, v18
	v_ldexp_f32 v20, v20, v21
	v_ldexp_f32 v19, v19, v21
	v_add_f32_e32 v21, -1.0, v20
	v_add_f32_e32 v22, 1.0, v20
	v_add_f32_e32 v23, 1.0, v21
	v_add_f32_e32 v24, -1.0, v22
	v_sub_f32_e32 v23, v20, v23
	v_sub_f32_e32 v20, v20, v24
	v_mul_f32_e32 v24, 0x3f317218, v18
	v_add_f32_e32 v23, v19, v23
	v_add_f32_e32 v19, v19, v20
	v_fma_f32 v20, v18, s34, -v24
	v_add_f32_e32 v25, v21, v23
	v_add_f32_e32 v26, v22, v19
	v_fmac_f32_e32 v20, 0xb102e308, v18
	v_sub_f32_e32 v18, v25, v21
	v_sub_f32_e32 v21, v26, v22
	v_rcp_f32_e32 v22, v26
	v_add_f32_e32 v27, v24, v20
	v_sub_f32_e32 v19, v19, v21
	v_sub_f32_e32 v21, v27, v24
	v_sub_f32_e32 v20, v20, v21
	v_mul_f32_e32 v21, v25, v22
	v_sub_f32_e32 v18, v23, v18
	v_mul_f32_e32 v23, v26, v21
	v_fma_f32 v24, v21, v26, -v23
	v_fmac_f32_e32 v24, v21, v19
	v_add_f32_e32 v28, v23, v24
	v_sub_f32_e32 v29, v25, v28
	v_sub_f32_e32 v23, v28, v23
	v_sub_f32_e32 v25, v25, v29
	v_sub_f32_e32 v23, v23, v24
	v_sub_f32_e32 v24, v25, v28
	v_add_f32_e32 v18, v18, v24
	v_add_f32_e32 v18, v23, v18
	v_add_f32_e32 v23, v29, v18
	v_mul_f32_e32 v24, v22, v23
	v_sub_f32_e32 v25, v29, v23
	v_mul_f32_e32 v28, v26, v24
	v_add_f32_e32 v18, v18, v25
	v_add_f32_e32 v25, v21, v24
	v_fma_f32 v26, v24, v26, -v28
	v_sub_f32_e32 v21, v25, v21
	v_fmac_f32_e32 v26, v24, v19
	v_sub_f32_e32 v19, v24, v21
	v_add_f32_e32 v21, v28, v26
	v_sub_f32_e32 v24, v21, v28
	v_sub_f32_e32 v28, v23, v21
	v_sub_f32_e32 v23, v23, v28
	v_sub_f32_e32 v21, v23, v21
	v_sub_f32_e32 v24, v24, v26
	v_add_f32_e32 v18, v18, v21
	v_add_f32_e32 v18, v24, v18
	v_add_f32_e32 v18, v28, v18
	v_mul_f32_e32 v18, v22, v18
	v_add_f32_e32 v18, v19, v18
	v_add_f32_e32 v19, v25, v18
	v_mul_f32_e32 v21, v19, v19
	v_fmac_f32_e32 v2, 0x3e9b6dac, v21
	v_sub_f32_e32 v22, v19, v25
	v_ldexp_f32 v23, v19, 1
	v_mul_f32_e32 v19, v19, v21
	v_fmac_f32_e32 v17, v21, v2
	v_sub_f32_e32 v18, v18, v22
	v_mul_f32_e32 v17, v19, v17
	v_ldexp_f32 v2, v18, 1
	v_add_f32_e32 v18, v23, v17
	v_sub_f32_e32 v19, v18, v23
	v_sub_f32_e32 v17, v17, v19
	v_add_f32_e32 v2, v2, v17
	v_add_f32_e32 v17, v18, v2
	v_sub_f32_e32 v18, v17, v18
	v_add_f32_e32 v19, v27, v17
	v_sub_f32_e32 v2, v2, v18
	v_sub_f32_e32 v18, v19, v27
	v_sub_f32_e32 v21, v19, v18
	v_sub_f32_e32 v17, v17, v18
	v_sub_f32_e32 v21, v27, v21
	v_add_f32_e32 v18, v20, v2
	v_add_f32_e32 v17, v17, v21
	v_sub_f32_e32 v22, v18, v20
	v_add_f32_e32 v17, v18, v17
	v_sub_f32_e32 v21, v18, v22
	v_add_f32_e32 v18, v19, v17
	v_sub_f32_e32 v2, v2, v22
	v_sub_f32_e32 v20, v20, v21
	v_sub_f32_e32 v19, v18, v19
	v_add_f32_e32 v2, v2, v20
	v_sub_f32_e32 v17, v17, v19
	v_add_f32_e32 v2, v2, v17
	v_add_f32_e32 v2, v18, v2
	v_cmp_neq_f32_e64 s[0:1], s23, v9
	s_nop 1
	v_cndmask_b32_e64 v2, v6, v2, s[0:1]
	v_cmp_ngt_f32_e64 s[0:1], -1.0, v9
	s_nop 1
	v_cndmask_b32_e64 v2, v7, v2, s[0:1]
	v_cmp_neq_f32_e64 s[0:1], -1.0, v9
	s_nop 1
	v_cndmask_b32_e64 v2, v8, v2, s[0:1]
	v_cmp_lt_f32_e64 s[0:1], |v9|, s33
	s_nop 1
	v_cndmask_b32_e64 v2, v2, v9, s[0:1]
	v_sub_f32_e32 v2, v3, v2
	v_mul_f32_e32 v3, 0x3fb8aa3b, v2
	ds_bpermute_b32 v6, v10, v3
	s_or_b32 s0, s22, 11
	s_ashr_i32 s1, s0, 31
	s_lshl_b64 s[28:29], s[0:1], 14
	v_mov_b32_e32 v7, s29
	s_waitcnt lgkmcnt(0)
	v_fmac_f32_e32 v6, 0x3fb8aa3b, v2
	v_cndmask_b32_e64 v2, v6, v3, s[2:3]
	ds_bpermute_b32 v3, v11, v2
	v_lshl_or_b32 v6, v12, 2, s28
	v_lshl_add_u64 v[8:9], s[20:21], 0, v[6:7]
	v_lshl_add_u64 v[6:7], s[26:27], 0, v[6:7]
	s_waitcnt lgkmcnt(0)
	v_add_f32_e32 v3, v2, v3
	v_cndmask_b32_e64 v2, v3, v2, s[8:9]
	ds_bpermute_b32 v3, v13, v2
	s_waitcnt lgkmcnt(0)
	v_add_f32_e32 v3, v2, v3
	v_cndmask_b32_e64 v2, v3, v2, s[10:11]
	ds_bpermute_b32 v3, v14, v2
	s_waitcnt lgkmcnt(0)
	v_add_f32_e32 v3, v2, v3
	v_cndmask_b32_e64 v2, v3, v2, s[6:7]
	ds_bpermute_b32 v3, v15, v2
	s_waitcnt lgkmcnt(0)
	v_add_f32_e32 v3, v2, v3
	v_cndmask_b32_e64 v3, v3, v2, s[12:13]
	ds_bpermute_b32 v2, v16, v3
	s_waitcnt lgkmcnt(0)
	v_add_f32_e32 v2, v3, v2
	v_cndmask_b32_e64 v3, v2, v3, s[4:5]
	global_store_dword v[8:9], v3, off
	v_xor_b32_e32 v3, 0x80000000, v3
	global_store_dword v[6:7], v3, off
	s_and_saveexec_b64 s[28:29], vcc
	s_cbranch_execz .LBB0_477
	s_lshl_b32 s0, s0, 6
	s_or_b32 s0, s0, s15
	s_ashr_i32 s1, s0, 31
	s_lshl_b64 s[0:1], s[0:1], 2
	s_add_u32 s0, s30, s0
	s_addc_u32 s1, s31, s1
	v_mov_b32_e32 v3, 0
	global_store_dword v3, v2, s[0:1]
; __global__ void __launch_bounds__(512, 2) fwd_kernel(Args a) {
;     ...
;             for (int hh = 0; hh < 16; ++hh) { const float z = fz[hh] + bfp[hh]; float incl = (fminf(z, 0.f) - log1pf(__expf(-fabsf(z)))) * LOG2E;
; #pragma unroll
;                 for (int o = 1; o < 64; o <<= 1) { const float t = __shfl_up(incl, o); if (lane >= o) incl += t; }
;                 cum[(size_t)(b * 16 + hh) * SEQ + ch * 64 + lane] = incl; ((float*)(ws + WS_NCUM))[(size_t)(b * 16 + hh) * SEQ + ch * 64 + lane] = -incl;
;                 if (lane == 63) totp[(b * 16 + hh) * 64 + ch] = incl; }
.LBB0_477:
	s_or_b64 exec, exec, s[28:29]
	v_mov_b32_e32 v8, 0
	v_mov_b32_e32 v7, v52
	v_lshlrev_b32_e32 v9, 16, v4
	v_mov_b32_e32 v2, 0x3ecc95a3
	v_mov_b32_e32 v3, 0x7f800000
	v_mov_b32_e32 v6, 0x7fc00000
	v_add_f32_e32 v9, v7, v9
	v_mul_f32_e64 v7, |v9|, s36
	v_exp_f32_e32 v17, v7
	v_mov_b32_e32 v7, 0xff800000
	v_min_f32_e32 v9, 0, v9
	v_add_f32_e32 v20, 1.0, v17
	v_add_f32_e32 v21, -1.0, v20
	v_frexp_mant_f32_e32 v22, v20
	v_cvt_f64_f32_e32 v[18:19], v20
	v_sub_f32_e32 v23, v21, v20
	v_frexp_exp_i32_f64_e32 v18, v[18:19]
	v_cmp_gt_f32_e64 s[0:1], s35, v22
	v_sub_f32_e32 v21, v17, v21
	v_add_f32_e32 v19, 1.0, v23
	v_subbrev_co_u32_e64 v18, s[0:1], 0, v18, s[0:1]
	v_add_f32_e32 v19, v21, v19
	v_sub_u32_e32 v21, 0, v18
	v_cvt_f32_i32_e32 v18, v18
	v_ldexp_f32 v20, v20, v21
	v_ldexp_f32 v19, v19, v21
	v_add_f32_e32 v21, -1.0, v20
	v_add_f32_e32 v22, 1.0, v20
	v_add_f32_e32 v23, 1.0, v21
	v_add_f32_e32 v24, -1.0, v22
	v_sub_f32_e32 v23, v20, v23
	v_sub_f32_e32 v20, v20, v24
	v_mul_f32_e32 v24, 0x3f317218, v18
	v_add_f32_e32 v23, v19, v23
	v_add_f32_e32 v19, v19, v20
	v_fma_f32 v20, v18, s34, -v24
	v_add_f32_e32 v25, v21, v23
	v_add_f32_e32 v26, v22, v19
	v_fmac_f32_e32 v20, 0xb102e308, v18
	v_sub_f32_e32 v18, v25, v21
	v_sub_f32_e32 v21, v26, v22
	v_rcp_f32_e32 v22, v26
	v_add_f32_e32 v27, v24, v20
	v_sub_f32_e32 v19, v19, v21
	v_sub_f32_e32 v21, v27, v24
	v_sub_f32_e32 v20, v20, v21
	v_mul_f32_e32 v21, v25, v22
	v_sub_f32_e32 v18, v23, v18
	v_mul_f32_e32 v23, v26, v21
	v_fma_f32 v24, v21, v26, -v23
	v_fmac_f32_e32 v24, v21, v19
	v_add_f32_e32 v28, v23, v24
	v_sub_f32_e32 v29, v25, v28
	v_sub_f32_e32 v23, v28, v23
	v_sub_f32_e32 v25, v25, v29
	v_sub_f32_e32 v23, v23, v24
	v_sub_f32_e32 v24, v25, v28
	v_add_f32_e32 v18, v18, v24
	v_add_f32_e32 v18, v23, v18
	v_add_f32_e32 v23, v29, v18
	v_mul_f32_e32 v24, v22, v23
	v_sub_f32_e32 v25, v29, v23
	v_mul_f32_e32 v28, v26, v24
	v_add_f32_e32 v18, v18, v25
	v_add_f32_e32 v25, v21, v24
	v_fma_f32 v26, v24, v26, -v28
	v_sub_f32_e32 v21, v25, v21
	v_fmac_f32_e32 v26, v24, v19
	v_sub_f32_e32 v19, v24, v21
	v_add_f32_e32 v21, v28, v26
	v_sub_f32_e32 v24, v21, v28
	v_sub_f32_e32 v28, v23, v21
	v_sub_f32_e32 v23, v23, v28
	v_sub_f32_e32 v21, v23, v21
	v_sub_f32_e32 v24, v24, v26
	v_add_f32_e32 v18, v18, v21
	v_add_f32_e32 v18, v24, v18
	v_add_f32_e32 v18, v28, v18
	v_mul_f32_e32 v18, v22, v18
	v_add_f32_e32 v18, v19, v18
	v_add_f32_e32 v19, v25, v18
	v_mul_f32_e32 v21, v19, v19
	v_fmamk_f32 v24, v21, 0x3e9b6dac, v2
	v_sub_f32_e32 v22, v19, v25
	v_ldexp_f32 v23, v19, 1
	v_mul_f32_e32 v19, v19, v21
	v_fmaak_f32 v21, v21, v24, 0x3f2aaada
	v_mul_f32_e32 v19, v19, v21
	v_add_f32_e32 v21, v23, v19
	v_sub_f32_e32 v18, v18, v22
	v_sub_f32_e32 v22, v21, v23
	v_ldexp_f32 v18, v18, 1
	v_sub_f32_e32 v19, v19, v22
	v_add_f32_e32 v18, v18, v19
	v_add_f32_e32 v19, v21, v18
	v_sub_f32_e32 v21, v19, v21
	v_add_f32_e32 v22, v27, v19
	v_sub_f32_e32 v18, v18, v21
	v_sub_f32_e32 v21, v22, v27
	v_sub_f32_e32 v23, v22, v21
	v_sub_f32_e32 v19, v19, v21
	v_add_f32_e32 v21, v20, v18
	v_sub_f32_e32 v23, v27, v23
	v_sub_f32_e32 v24, v21, v20
	v_add_f32_e32 v19, v19, v23
	v_sub_f32_e32 v23, v21, v24
	v_sub_f32_e32 v18, v18, v24
	v_sub_f32_e32 v20, v20, v23
	v_add_f32_e32 v19, v21, v19
	v_add_f32_e32 v18, v18, v20
	v_add_f32_e32 v20, v22, v19
	v_sub_f32_e32 v21, v20, v22
	v_sub_f32_e32 v19, v19, v21
	v_add_f32_e32 v18, v18, v19
	v_add_f32_e32 v18, v20, v18
	v_cmp_neq_f32_e64 s[0:1], s23, v17
	s_nop 1
	v_cndmask_b32_e64 v18, v3, v18, s[0:1]
	v_cmp_ngt_f32_e64 s[0:1], -1.0, v17
	s_nop 1
	v_cndmask_b32_e64 v18, v6, v18, s[0:1]
	v_cmp_neq_f32_e64 s[0:1], -1.0, v17
	s_nop 1
	v_cndmask_b32_e64 v18, v7, v18, s[0:1]
	v_cmp_lt_f32_e64 s[0:1], |v17|, s33
	s_nop 1
	v_cndmask_b32_e64 v17, v18, v17, s[0:1]
	v_sub_f32_e32 v9, v9, v17
	v_mul_f32_e32 v17, 0x3fb8aa3b, v9
	ds_bpermute_b32 v18, v10, v17
	s_or_b32 s0, s22, 12
	s_ashr_i32 s1, s0, 31
	s_lshl_b64 s[28:29], s[0:1], 14
	v_mov_b32_e32 v19, s29
	s_waitcnt lgkmcnt(0)
	v_fmac_f32_e32 v18, 0x3fb8aa3b, v9
	v_cndmask_b32_e64 v9, v18, v17, s[2:3]
	ds_bpermute_b32 v17, v11, v9
	s_waitcnt lgkmcnt(0)
	v_add_f32_e32 v17, v9, v17
	v_cndmask_b32_e64 v9, v17, v9, s[8:9]
	ds_bpermute_b32 v17, v13, v9
	s_waitcnt lgkmcnt(0)
	v_add_f32_e32 v17, v9, v17
	v_cndmask_b32_e64 v9, v17, v9, s[10:11]
	ds_bpermute_b32 v17, v14, v9
	s_waitcnt lgkmcnt(0)
	v_add_f32_e32 v17, v9, v17
	v_cndmask_b32_e64 v17, v17, v9, s[6:7]
	ds_bpermute_b32 v18, v15, v17
	v_mov_b32_e32 v9, 0x3f2aaada
	s_waitcnt lgkmcnt(0)
	v_add_f32_e32 v18, v17, v18
	v_cndmask_b32_e64 v22, v18, v17, s[12:13]
	ds_bpermute_b32 v17, v16, v22
	v_lshl_or_b32 v18, v12, 2, s28
	v_lshl_add_u64 v[20:21], s[20:21], 0, v[18:19]
	v_lshl_add_u64 v[18:19], s[26:27], 0, v[18:19]
	s_waitcnt lgkmcnt(0)
	v_add_f32_e32 v17, v22, v17
	v_cndmask_b32_e64 v22, v17, v22, s[4:5]
	global_store_dword v[20:21], v22, off
	v_xor_b32_e32 v20, 0x80000000, v22
	global_store_dword v[18:19], v20, off
	s_and_saveexec_b64 s[28:29], vcc
	s_cbranch_execz .LBB0_479
	s_lshl_b32 s0, s0, 6
	s_or_b32 s0, s0, s15
	s_ashr_i32 s1, s0, 31
	s_lshl_b64 s[0:1], s[0:1], 2
	s_add_u32 s0, s30, s0
	s_addc_u32 s1, s31, s1
	global_store_dword v8, v17, s[0:1]
; __global__ void __launch_bounds__(512, 2) fwd_kernel(Args a) {
;     ...
;             for (int hh = 0; hh < 16; ++hh) { const float z = fz[hh] + bfp[hh]; float incl = (fminf(z, 0.f) - log1pf(__expf(-fabsf(z)))) * LOG2E;
; #pragma unroll
;                 for (int o = 1; o < 64; o <<= 1) { const float t = __shfl_up(incl, o); if (lane >= o) incl += t; }
;                 cum[(size_t)(b * 16 + hh) * SEQ + ch * 64 + lane] = incl; ((float*)(ws + WS_NCUM))[(size_t)(b * 16 + hh) * SEQ + ch * 64 + lane] = -incl;
;                 if (lane == 63) totp[(b * 16 + hh) * 64 + ch] = incl; }
.LBB0_479:
	s_or_b64 exec, exec, s[28:29]
	v_mov_b32_e32 v8, v53
	v_and_b32_e32 v4, 0xffff0000, v4
	v_add_f32_e32 v4, v8, v4
	v_mul_f32_e64 v8, |v4|, s36
	v_exp_f32_e32 v8, v8
	v_min_f32_e32 v4, 0, v4
	v_add_f32_e32 v17, 1.0, v8
	v_add_f32_e32 v20, -1.0, v17
	v_frexp_mant_f32_e32 v21, v17
	v_cvt_f64_f32_e32 v[18:19], v17
	v_sub_f32_e32 v22, v20, v17
	v_frexp_exp_i32_f64_e32 v18, v[18:19]
	v_cmp_gt_f32_e64 s[0:1], s35, v21
	v_sub_f32_e32 v20, v8, v20
	v_add_f32_e32 v19, 1.0, v22
	v_subbrev_co_u32_e64 v18, s[0:1], 0, v18, s[0:1]
	v_add_f32_e32 v19, v20, v19
	v_sub_u32_e32 v20, 0, v18
	v_cvt_f32_i32_e32 v18, v18
	v_ldexp_f32 v17, v17, v20
	v_ldexp_f32 v19, v19, v20
	v_add_f32_e32 v20, -1.0, v17
	v_add_f32_e32 v21, 1.0, v17
	v_add_f32_e32 v22, 1.0, v20
	v_add_f32_e32 v23, -1.0, v21
	v_sub_f32_e32 v22, v17, v22
	v_sub_f32_e32 v17, v17, v23
	v_mul_f32_e32 v23, 0x3f317218, v18
	v_add_f32_e32 v22, v19, v22
	v_add_f32_e32 v17, v19, v17
	v_fma_f32 v19, v18, s34, -v23
	v_add_f32_e32 v24, v20, v22
	v_add_f32_e32 v25, v21, v17
	v_fmac_f32_e32 v19, 0xb102e308, v18
	v_sub_f32_e32 v18, v24, v20
	v_sub_f32_e32 v20, v25, v21
	v_rcp_f32_e32 v21, v25
	v_add_f32_e32 v26, v23, v19
	v_sub_f32_e32 v17, v17, v20
	v_sub_f32_e32 v20, v26, v23
	v_sub_f32_e32 v19, v19, v20
	v_mul_f32_e32 v20, v24, v21
	v_sub_f32_e32 v18, v22, v18
	v_mul_f32_e32 v22, v25, v20
	v_fma_f32 v23, v20, v25, -v22
	v_fmac_f32_e32 v23, v20, v17
	v_add_f32_e32 v27, v22, v23
	v_sub_f32_e32 v28, v24, v27
	v_sub_f32_e32 v22, v27, v22
	v_sub_f32_e32 v24, v24, v28
	v_sub_f32_e32 v22, v22, v23
	v_sub_f32_e32 v23, v24, v27
	v_add_f32_e32 v18, v18, v23
	v_add_f32_e32 v18, v22, v18
	v_add_f32_e32 v22, v28, v18
	v_mul_f32_e32 v23, v21, v22
	v_sub_f32_e32 v24, v28, v22
	v_mul_f32_e32 v27, v25, v23
	v_add_f32_e32 v18, v18, v24
	v_add_f32_e32 v24, v20, v23
	v_fma_f32 v25, v23, v25, -v27
	v_sub_f32_e32 v20, v24, v20
	v_fmac_f32_e32 v25, v23, v17
	v_sub_f32_e32 v17, v23, v20
	v_add_f32_e32 v20, v27, v25
	v_sub_f32_e32 v23, v20, v27
	v_sub_f32_e32 v27, v22, v20
	v_sub_f32_e32 v22, v22, v27
	v_sub_f32_e32 v20, v22, v20
	v_sub_f32_e32 v23, v23, v25
	v_add_f32_e32 v18, v18, v20
	v_add_f32_e32 v18, v23, v18
	v_add_f32_e32 v18, v27, v18
	v_mul_f32_e32 v18, v21, v18
	v_add_f32_e32 v17, v17, v18
	v_add_f32_e32 v18, v24, v17
	v_mul_f32_e32 v20, v18, v18
	v_fmac_f32_e32 v2, 0x3e9b6dac, v20
	v_sub_f32_e32 v21, v18, v24
	v_ldexp_f32 v22, v18, 1
	v_mul_f32_e32 v18, v18, v20
	v_fmac_f32_e32 v9, v20, v2
	v_sub_f32_e32 v17, v17, v21
	v_mul_f32_e32 v9, v18, v9
	v_ldexp_f32 v2, v17, 1
	v_add_f32_e32 v17, v22, v9
	v_sub_f32_e32 v18, v17, v22
	v_sub_f32_e32 v9, v9, v18
	v_add_f32_e32 v2, v2, v9
	v_add_f32_e32 v9, v17, v2
	v_sub_f32_e32 v17, v9, v17
	v_add_f32_e32 v18, v26, v9
	v_sub_f32_e32 v2, v2, v17
	v_sub_f32_e32 v17, v18, v26
	v_sub_f32_e32 v20, v18, v17
	v_sub_f32_e32 v9, v9, v17
	v_sub_f32_e32 v20, v26, v20
	v_add_f32_e32 v17, v19, v2
	v_add_f32_e32 v9, v9, v20
	v_sub_f32_e32 v21, v17, v19
	v_add_f32_e32 v9, v17, v9
	v_sub_f32_e32 v20, v17, v21
	v_add_f32_e32 v17, v18, v9
	v_sub_f32_e32 v2, v2, v21
	v_sub_f32_e32 v19, v19, v20
	v_sub_f32_e32 v18, v17, v18
	v_add_f32_e32 v2, v2, v19
	v_sub_f32_e32 v9, v9, v18
	v_add_f32_e32 v2, v2, v9
	v_add_f32_e32 v2, v17, v2
	v_cmp_neq_f32_e64 s[0:1], s23, v8
	s_nop 1
	v_cndmask_b32_e64 v2, v3, v2, s[0:1]
	v_cmp_ngt_f32_e64 s[0:1], -1.0, v8
	s_nop 1
	v_cndmask_b32_e64 v2, v6, v2, s[0:1]
	v_cmp_neq_f32_e64 s[0:1], -1.0, v8
	s_nop 1
	v_cndmask_b32_e64 v2, v7, v2, s[0:1]
	v_cmp_lt_f32_e64 s[0:1], |v8|, s33
	s_nop 1
	v_cndmask_b32_e64 v2, v2, v8, s[0:1]
	v_sub_f32_e32 v2, v4, v2
	v_mul_f32_e32 v3, 0x3fb8aa3b, v2
	ds_bpermute_b32 v4, v10, v3
	s_or_b32 s0, s22, 13
	s_ashr_i32 s1, s0, 31
	s_lshl_b64 s[28:29], s[0:1], 14
	v_lshl_or_b32 v6, v12, 2, s28
	s_waitcnt lgkmcnt(0)
	v_fmac_f32_e32 v4, 0x3fb8aa3b, v2
	v_cndmask_b32_e64 v2, v4, v3, s[2:3]
	ds_bpermute_b32 v3, v11, v2
	v_mov_b32_e32 v7, s29
	v_lshl_add_u64 v[8:9], s[20:21], 0, v[6:7]
	v_lshl_add_u64 v[6:7], s[26:27], 0, v[6:7]
	s_waitcnt lgkmcnt(0)
	v_add_f32_e32 v3, v2, v3
	v_cndmask_b32_e64 v2, v3, v2, s[8:9]
	ds_bpermute_b32 v3, v13, v2
	s_waitcnt lgkmcnt(0)
	v_add_f32_e32 v3, v2, v3
	v_cndmask_b32_e64 v2, v3, v2, s[10:11]
	ds_bpermute_b32 v3, v14, v2
	s_waitcnt lgkmcnt(0)
	v_add_f32_e32 v3, v2, v3
	v_cndmask_b32_e64 v2, v3, v2, s[6:7]
	ds_bpermute_b32 v3, v15, v2
	s_waitcnt lgkmcnt(0)
	v_add_f32_e32 v3, v2, v3
	v_cndmask_b32_e64 v3, v3, v2, s[12:13]
	ds_bpermute_b32 v2, v16, v3
	s_waitcnt lgkmcnt(0)
	v_add_f32_e32 v2, v3, v2
	v_cndmask_b32_e64 v3, v2, v3, s[4:5]
	global_store_dword v[8:9], v3, off
	v_xor_b32_e32 v3, 0x80000000, v3
	global_store_dword v[6:7], v3, off
	s_and_saveexec_b64 s[28:29], vcc
	s_cbranch_execz .LBB0_481
	s_lshl_b32 s0, s0, 6
	s_or_b32 s0, s0, s15
	s_ashr_i32 s1, s0, 31
	s_lshl_b64 s[0:1], s[0:1], 2
	s_add_u32 s0, s30, s0
	s_addc_u32 s1, s31, s1
	v_mov_b32_e32 v3, 0
	global_store_dword v3, v2, s[0:1]
; __global__ void __launch_bounds__(512, 2) fwd_kernel(Args a) {
;     ...
;             for (int hh = 0; hh < 16; ++hh) { const float z = fz[hh] + bfp[hh]; float incl = (fminf(z, 0.f) - log1pf(__expf(-fabsf(z)))) * LOG2E;
; #pragma unroll
;                 for (int o = 1; o < 64; o <<= 1) { const float t = __shfl_up(incl, o); if (lane >= o) incl += t; }
;                 cum[(size_t)(b * 16 + hh) * SEQ + ch * 64 + lane] = incl; ((float*)(ws + WS_NCUM))[(size_t)(b * 16 + hh) * SEQ + ch * 64 + lane] = -incl;
;                 if (lane == 63) totp[(b * 16 + hh) * 64 + ch] = incl; }
.LBB0_481:
	s_or_b64 exec, exec, s[28:29]
	v_mov_b32_e32 v7, 0
	v_mov_b32_e32 v6, v54
	v_lshlrev_b32_e32 v8, 16, v5
	v_mov_b32_e32 v2, 0x3ecc95a3
	v_mov_b32_e32 v3, 0x7f800000
	v_mov_b32_e32 v4, 0x7fc00000
	v_add_f32_e32 v8, v6, v8
	v_mul_f32_e64 v6, |v8|, s36
	v_exp_f32_e32 v17, v6
	v_min_f32_e32 v18, 0, v8
	v_mov_b32_e32 v6, 0xff800000
	v_add_f32_e32 v19, 1.0, v17
	v_add_f32_e32 v20, -1.0, v19
	v_frexp_mant_f32_e32 v21, v19
	v_cvt_f64_f32_e32 v[8:9], v19
	v_sub_f32_e32 v22, v20, v19
	v_frexp_exp_i32_f64_e32 v8, v[8:9]
	v_cmp_gt_f32_e64 s[0:1], s35, v21
	v_sub_f32_e32 v20, v17, v20
	v_add_f32_e32 v9, 1.0, v22
	v_subbrev_co_u32_e64 v8, s[0:1], 0, v8, s[0:1]
	v_add_f32_e32 v9, v20, v9
	v_sub_u32_e32 v20, 0, v8
	v_cvt_f32_i32_e32 v8, v8
	v_ldexp_f32 v19, v19, v20
	v_ldexp_f32 v9, v9, v20
	v_add_f32_e32 v20, -1.0, v19
	v_add_f32_e32 v21, 1.0, v19
	v_add_f32_e32 v22, 1.0, v20
	v_add_f32_e32 v23, -1.0, v21
	v_sub_f32_e32 v22, v19, v22
	v_sub_f32_e32 v19, v19, v23
	v_mul_f32_e32 v23, 0x3f317218, v8
	v_add_f32_e32 v22, v9, v22
	v_add_f32_e32 v9, v9, v19
	v_fma_f32 v19, v8, s34, -v23
	v_add_f32_e32 v24, v20, v22
	v_add_f32_e32 v25, v21, v9
	v_fmac_f32_e32 v19, 0xb102e308, v8
	v_sub_f32_e32 v8, v24, v20
	v_sub_f32_e32 v20, v25, v21
	v_rcp_f32_e32 v21, v25
	v_add_f32_e32 v26, v23, v19
	v_sub_f32_e32 v9, v9, v20
	v_sub_f32_e32 v20, v26, v23
	v_sub_f32_e32 v19, v19, v20
	v_mul_f32_e32 v20, v24, v21
	v_sub_f32_e32 v8, v22, v8
	v_mul_f32_e32 v22, v25, v20
	v_fma_f32 v23, v20, v25, -v22
	v_fmac_f32_e32 v23, v20, v9
	v_add_f32_e32 v27, v22, v23
	v_sub_f32_e32 v28, v24, v27
	v_sub_f32_e32 v22, v27, v22
	v_sub_f32_e32 v24, v24, v28
	v_sub_f32_e32 v22, v22, v23
	v_sub_f32_e32 v23, v24, v27
	v_add_f32_e32 v8, v8, v23
	v_add_f32_e32 v8, v22, v8
	v_add_f32_e32 v22, v28, v8
	v_mul_f32_e32 v23, v21, v22
	v_sub_f32_e32 v24, v28, v22
	v_mul_f32_e32 v27, v25, v23
	v_add_f32_e32 v8, v8, v24
	v_add_f32_e32 v24, v20, v23
	v_fma_f32 v25, v23, v25, -v27
	v_sub_f32_e32 v20, v24, v20
	v_fmac_f32_e32 v25, v23, v9
	v_sub_f32_e32 v9, v23, v20
	v_add_f32_e32 v20, v27, v25
	v_sub_f32_e32 v23, v20, v27
	v_sub_f32_e32 v27, v22, v20
	v_sub_f32_e32 v22, v22, v27
	v_sub_f32_e32 v20, v22, v20
	v_sub_f32_e32 v23, v23, v25
	v_add_f32_e32 v8, v8, v20
	v_add_f32_e32 v8, v23, v8
	v_add_f32_e32 v8, v27, v8
	v_mul_f32_e32 v8, v21, v8
	v_add_f32_e32 v8, v9, v8
	v_add_f32_e32 v9, v24, v8
	v_mul_f32_e32 v20, v9, v9
	v_fmamk_f32 v23, v20, 0x3e9b6dac, v2
	v_sub_f32_e32 v21, v9, v24
	v_ldexp_f32 v22, v9, 1
	v_mul_f32_e32 v9, v9, v20
	v_fmaak_f32 v20, v20, v23, 0x3f2aaada
	v_mul_f32_e32 v9, v9, v20
	v_add_f32_e32 v20, v22, v9
	v_sub_f32_e32 v8, v8, v21
	v_sub_f32_e32 v21, v20, v22
	v_ldexp_f32 v8, v8, 1
	v_sub_f32_e32 v9, v9, v21
	v_add_f32_e32 v8, v8, v9
	v_add_f32_e32 v9, v20, v8
	v_sub_f32_e32 v20, v9, v20
	v_add_f32_e32 v21, v26, v9
	v_sub_f32_e32 v8, v8, v20
	v_sub_f32_e32 v20, v21, v26
	v_sub_f32_e32 v22, v21, v20
	v_sub_f32_e32 v9, v9, v20
	v_add_f32_e32 v20, v19, v8
	v_sub_f32_e32 v22, v26, v22
	v_sub_f32_e32 v23, v20, v19
	v_add_f32_e32 v9, v9, v22
	v_sub_f32_e32 v22, v20, v23
	v_sub_f32_e32 v8, v8, v23
	v_sub_f32_e32 v19, v19, v22
	v_add_f32_e32 v9, v20, v9
	v_add_f32_e32 v8, v8, v19
	v_add_f32_e32 v19, v21, v9
	v_sub_f32_e32 v20, v19, v21
	v_sub_f32_e32 v9, v9, v20
	v_add_f32_e32 v8, v8, v9
	v_add_f32_e32 v8, v19, v8
	v_cmp_neq_f32_e64 s[0:1], s23, v17
	s_nop 1
	v_cndmask_b32_e64 v8, v3, v8, s[0:1]
	v_cmp_ngt_f32_e64 s[0:1], -1.0, v17
	s_nop 1
	v_cndmask_b32_e64 v8, v4, v8, s[0:1]
	v_cmp_neq_f32_e64 s[0:1], -1.0, v17
	s_nop 1
	v_cndmask_b32_e64 v8, v6, v8, s[0:1]
	v_cmp_lt_f32_e64 s[0:1], |v17|, s33
	s_nop 1
	v_cndmask_b32_e64 v8, v8, v17, s[0:1]
	v_sub_f32_e32 v8, v18, v8
	v_mul_f32_e32 v9, 0x3fb8aa3b, v8
	ds_bpermute_b32 v17, v10, v9
	s_or_b32 s0, s22, 14
	s_ashr_i32 s1, s0, 31
	s_lshl_b64 s[28:29], s[0:1], 14
	v_lshl_or_b32 v18, v12, 2, s28
	s_waitcnt lgkmcnt(0)
	v_fmac_f32_e32 v17, 0x3fb8aa3b, v8
	v_cndmask_b32_e64 v8, v17, v9, s[2:3]
	ds_bpermute_b32 v9, v11, v8
	v_mov_b32_e32 v19, s29
	v_lshl_add_u64 v[20:21], s[20:21], 0, v[18:19]
	v_lshl_add_u64 v[18:19], s[26:27], 0, v[18:19]
	s_waitcnt lgkmcnt(0)
	v_add_f32_e32 v9, v8, v9
	v_cndmask_b32_e64 v8, v9, v8, s[8:9]
	ds_bpermute_b32 v9, v13, v8
	s_waitcnt lgkmcnt(0)
	v_add_f32_e32 v9, v8, v9
	v_cndmask_b32_e64 v8, v9, v8, s[10:11]
	ds_bpermute_b32 v9, v14, v8
	s_waitcnt lgkmcnt(0)
	v_add_f32_e32 v9, v8, v9
	v_cndmask_b32_e64 v9, v9, v8, s[6:7]
	ds_bpermute_b32 v17, v15, v9
	v_mov_b32_e32 v8, 0x3f2aaada
	s_waitcnt lgkmcnt(0)
	v_add_f32_e32 v17, v9, v17
	v_cndmask_b32_e64 v17, v17, v9, s[12:13]
	ds_bpermute_b32 v9, v16, v17
	s_waitcnt lgkmcnt(0)
	v_add_f32_e32 v9, v17, v9
	v_cndmask_b32_e64 v17, v9, v17, s[4:5]
	global_store_dword v[20:21], v17, off
	v_xor_b32_e32 v17, 0x80000000, v17
	global_store_dword v[18:19], v17, off
	s_and_saveexec_b64 s[28:29], vcc
	s_cbranch_execz .LBB0_483
	s_lshl_b32 s0, s0, 6
	s_or_b32 s0, s0, s15
	s_ashr_i32 s1, s0, 31
	s_lshl_b64 s[0:1], s[0:1], 2
	s_add_u32 s0, s30, s0
	s_addc_u32 s1, s31, s1
	global_store_dword v7, v9, s[0:1]
; __global__ void __launch_bounds__(512, 2) fwd_kernel(Args a) {
;     ...
;             for (int hh = 0; hh < 16; ++hh) { const float z = fz[hh] + bfp[hh]; float incl = (fminf(z, 0.f) - log1pf(__expf(-fabsf(z)))) * LOG2E;
; #pragma unroll
;                 for (int o = 1; o < 64; o <<= 1) { const float t = __shfl_up(incl, o); if (lane >= o) incl += t; }
;                 cum[(size_t)(b * 16 + hh) * SEQ + ch * 64 + lane] = incl; ((float*)(ws + WS_NCUM))[(size_t)(b * 16 + hh) * SEQ + ch * 64 + lane] = -incl;
;                 if (lane == 63) totp[(b * 16 + hh) * 64 + ch] = incl; }
.LBB0_483:
	s_or_b64 exec, exec, s[28:29]
	v_mov_b32_e32 v7, v55
	v_and_b32_e32 v5, 0xffff0000, v5
	v_add_f32_e32 v5, v7, v5
	v_mul_f32_e64 v7, |v5|, s36
	v_exp_f32_e32 v7, v7
	v_min_f32_e32 v5, 0, v5
	v_add_f32_e32 v9, 1.0, v7
	v_add_f32_e32 v17, -1.0, v9
	v_frexp_mant_f32_e32 v20, v9
	v_cvt_f64_f32_e32 v[18:19], v9
	v_sub_f32_e32 v21, v17, v9
	v_frexp_exp_i32_f64_e32 v18, v[18:19]
	v_cmp_gt_f32_e64 s[0:1], s35, v20
	v_sub_f32_e32 v17, v7, v17
	v_add_f32_e32 v19, 1.0, v21
	v_subbrev_co_u32_e64 v18, s[0:1], 0, v18, s[0:1]
	v_add_f32_e32 v17, v17, v19
	v_sub_u32_e32 v19, 0, v18
	v_cvt_f32_i32_e32 v18, v18
	v_ldexp_f32 v9, v9, v19
	v_ldexp_f32 v17, v17, v19
	v_add_f32_e32 v19, -1.0, v9
	v_add_f32_e32 v20, 1.0, v9
	v_add_f32_e32 v21, 1.0, v19
	v_add_f32_e32 v22, -1.0, v20
	v_sub_f32_e32 v21, v9, v21
	v_sub_f32_e32 v9, v9, v22
	v_mul_f32_e32 v22, 0x3f317218, v18
	v_add_f32_e32 v21, v17, v21
	v_add_f32_e32 v9, v17, v9
	v_fma_f32 v17, v18, s34, -v22
	v_add_f32_e32 v23, v19, v21
	v_add_f32_e32 v24, v20, v9
	v_fmac_f32_e32 v17, 0xb102e308, v18
	v_sub_f32_e32 v18, v23, v19
	v_sub_f32_e32 v19, v24, v20
	v_rcp_f32_e32 v20, v24
	v_add_f32_e32 v25, v22, v17
	v_sub_f32_e32 v9, v9, v19
	v_sub_f32_e32 v19, v25, v22
	v_sub_f32_e32 v17, v17, v19
	v_mul_f32_e32 v19, v23, v20
	v_sub_f32_e32 v18, v21, v18
	v_mul_f32_e32 v21, v24, v19
	v_fma_f32 v22, v19, v24, -v21
	v_fmac_f32_e32 v22, v19, v9
	v_add_f32_e32 v26, v21, v22
	v_sub_f32_e32 v27, v23, v26
	v_sub_f32_e32 v21, v26, v21
	v_sub_f32_e32 v23, v23, v27
	v_sub_f32_e32 v21, v21, v22
	v_sub_f32_e32 v22, v23, v26
	v_add_f32_e32 v18, v18, v22
	v_add_f32_e32 v18, v21, v18
	v_add_f32_e32 v21, v27, v18
	v_mul_f32_e32 v22, v20, v21
	v_sub_f32_e32 v23, v27, v21
	v_mul_f32_e32 v26, v24, v22
	v_add_f32_e32 v18, v18, v23
	v_add_f32_e32 v23, v19, v22
	v_fma_f32 v24, v22, v24, -v26
	v_sub_f32_e32 v19, v23, v19
	v_fmac_f32_e32 v24, v22, v9
	v_sub_f32_e32 v9, v22, v19
	v_add_f32_e32 v19, v26, v24
	v_sub_f32_e32 v22, v19, v26
	v_sub_f32_e32 v26, v21, v19
	v_sub_f32_e32 v21, v21, v26
	v_sub_f32_e32 v19, v21, v19
	v_sub_f32_e32 v22, v22, v24
	v_add_f32_e32 v18, v18, v19
	v_add_f32_e32 v18, v22, v18
	v_add_f32_e32 v18, v26, v18
	v_mul_f32_e32 v18, v20, v18
	v_add_f32_e32 v9, v9, v18
	v_add_f32_e32 v18, v23, v9
	v_mul_f32_e32 v19, v18, v18
	v_fmac_f32_e32 v2, 0x3e9b6dac, v19
	v_sub_f32_e32 v20, v18, v23
	v_ldexp_f32 v21, v18, 1
	v_mul_f32_e32 v18, v18, v19
	v_fmac_f32_e32 v8, v19, v2
	v_sub_f32_e32 v9, v9, v20
	v_mul_f32_e32 v8, v18, v8
	v_ldexp_f32 v2, v9, 1
	v_add_f32_e32 v9, v21, v8
	v_sub_f32_e32 v18, v9, v21
	v_sub_f32_e32 v8, v8, v18
	v_add_f32_e32 v2, v2, v8
	v_add_f32_e32 v8, v9, v2
	v_sub_f32_e32 v9, v8, v9
	v_add_f32_e32 v18, v25, v8
	v_sub_f32_e32 v2, v2, v9
	v_sub_f32_e32 v9, v18, v25
	v_sub_f32_e32 v19, v18, v9
	v_sub_f32_e32 v8, v8, v9
	v_add_f32_e32 v9, v17, v2
	v_sub_f32_e32 v19, v25, v19
	v_sub_f32_e32 v20, v9, v17
	v_add_f32_e32 v8, v8, v19
	v_sub_f32_e32 v19, v9, v20
	v_add_f32_e32 v8, v9, v8
	v_sub_f32_e32 v2, v2, v20
	v_sub_f32_e32 v17, v17, v19
	v_add_f32_e32 v9, v18, v8
	v_add_f32_e32 v2, v2, v17
	v_sub_f32_e32 v17, v9, v18
	v_sub_f32_e32 v8, v8, v17
	v_add_f32_e32 v2, v2, v8
	v_add_f32_e32 v2, v9, v2
	v_cmp_neq_f32_e64 s[0:1], s23, v7
	s_nop 1
	v_cndmask_b32_e64 v2, v3, v2, s[0:1]
	v_cmp_ngt_f32_e64 s[0:1], -1.0, v7
	s_nop 1
	v_cndmask_b32_e64 v2, v4, v2, s[0:1]
	v_cmp_neq_f32_e64 s[0:1], -1.0, v7
	s_nop 1
	v_cndmask_b32_e64 v2, v6, v2, s[0:1]
	v_cmp_lt_f32_e64 s[0:1], |v7|, s33
	s_nop 1
	v_cndmask_b32_e64 v2, v2, v7, s[0:1]
	v_sub_f32_e32 v2, v5, v2
	v_mul_f32_e32 v3, 0x3fb8aa3b, v2
	ds_bpermute_b32 v4, v10, v3
	s_or_b32 s0, s22, 15
	s_ashr_i32 s1, s0, 31
	s_waitcnt lgkmcnt(0)
	v_fmac_f32_e32 v4, 0x3fb8aa3b, v2
	v_cndmask_b32_e64 v2, v4, v3, s[2:3]
	ds_bpermute_b32 v3, v11, v2
	s_waitcnt lgkmcnt(0)
	v_add_f32_e32 v3, v2, v3
	v_cndmask_b32_e64 v2, v3, v2, s[8:9]
	ds_bpermute_b32 v3, v13, v2
	s_lshl_b64 s[8:9], s[0:1], 14
	v_lshl_or_b32 v4, v12, 2, s8
	v_mov_b32_e32 v5, s9
	v_lshl_add_u64 v[6:7], s[20:21], 0, v[4:5]
	s_waitcnt lgkmcnt(0)
	v_add_f32_e32 v3, v2, v3
	v_cndmask_b32_e64 v2, v3, v2, s[10:11]
	ds_bpermute_b32 v3, v14, v2
	v_lshl_add_u64 v[4:5], s[26:27], 0, v[4:5]
	s_waitcnt lgkmcnt(0)
	v_add_f32_e32 v3, v2, v3
	v_cndmask_b32_e64 v2, v3, v2, s[6:7]
	ds_bpermute_b32 v3, v15, v2
	s_waitcnt lgkmcnt(0)
	v_add_f32_e32 v3, v2, v3
	v_cndmask_b32_e64 v3, v3, v2, s[12:13]
	ds_bpermute_b32 v2, v16, v3
	s_waitcnt lgkmcnt(0)
	v_add_f32_e32 v2, v3, v2
	v_cndmask_b32_e64 v3, v2, v3, s[4:5]
	global_store_dword v[6:7], v3, off
	v_xor_b32_e32 v3, 0x80000000, v3
	global_store_dword v[4:5], v3, off
	s_and_saveexec_b64 s[8:9], vcc
	s_cbranch_execz .LBB0_485
	s_lshl_b32 s0, s0, 6
	s_or_b32 s0, s0, s15
	s_ashr_i32 s1, s0, 31
	s_lshl_b64 s[0:1], s[0:1], 2
	s_add_u32 s0, s30, s0
	s_addc_u32 s1, s31, s1
	v_mov_b32_e32 v3, 0
	global_store_dword v3, v2, s[0:1]

; __global__ void __launch_bounds__(512, 2) fwd_kernel(Args a) {
;     ...
;         for (int m = gw; m < MTOK; m += NGW) {
;             const bf16_t* pr = proj + (size_t)m * NPROJ;
;             { const u32x4 v = *(const u32x4*)(pr + PC_CQ + lane * 8); float s = 0.f;
;               s += bflo(v.x) * bflo(v.x) + bfhi(v.x) * bfhi(v.x) + bflo(v.y) * bflo(v.y) + bfhi(v.y) * bfhi(v.y) + bflo(v.z) * bflo(v.z) + bfhi(v.z) * bfhi(v.z) + bflo(v.w) * bflo(v.w) + bfhi(v.w) * bfhi(v.w);
;               s = wave_sum(s); if (lane == 0) rstd_q[m] = 1.0f / sqrtf(s * (1.0f / 512.0f) + RMS_EPS); }
;             { float s = 0.f; if (lane < 32) { const u32x4 v = *(const u32x4*)(pr + PC_CKV + lane * 8);
;               s += bflo(v.x) * bflo(v.x) + bfhi(v.x) * bfhi(v.x) + bflo(v.y) * bflo(v.y) + bfhi(v.y) * bfhi(v.y) + bflo(v.z) * bflo(v.z) + bfhi(v.z) * bfhi(v.z) + bflo(v.w) * bflo(v.w) + bfhi(v.w) * bfhi(v.w); }
;               s = wave_sum(s); if (lane == 0) rstd_kv[m] = 1.0f / sqrtf(s * (1.0f / 256.0f) + RMS_EPS); }
;             if (lane < 8) { const u32x4 v = *(const u32x4*)(pr + PC_KR + lane * 8); const int pos = m & (SEQ - 1), i0 = lane * 4;
.LBB0_486:
	s_cmpk_gt_i32 s96, 0x1fff
	s_cbranch_scc1 .LBB0_497
	s_cmp_lt_u32 s96, 0x80
	s_cbranch_scc1 .LBB0_497
	s_sub_i32 s98, s96, 0x80
	s_mov_b32 s99, 0
	s_movk_i32 s100, 0x780
	s_mov_b32 s101, 0
	v_mbcnt_lo_u32_b32 v2, -1, 0
	v_mbcnt_hi_u32_b32 v2, -1, v2
	v_and_b32_e32 v3, 64, v2
	v_add_u32_e32 v3, 64, v3
	v_xor_b32_e32 v4, 1, v2
	v_cmp_lt_i32_e32 vcc, v4, v3
	v_lshlrev_b32_e32 v8, 4, v196
	v_mov_b32_e32 v9, 0
	v_cndmask_b32_e32 v4, v2, v4, vcc
	v_lshlrev_b32_e32 v12, 2, v4
	v_xor_b32_e32 v4, 2, v2
	v_cmp_lt_i32_e32 vcc, v4, v3
	s_mov_b64 s[0:1], 0x500000
	v_cndmask_b32_e32 v4, v2, v4, vcc
	v_lshlrev_b32_e32 v13, 2, v4
	v_xor_b32_e32 v4, 4, v2
	v_cmp_lt_i32_e32 vcc, v4, v3
	s_mov_b32 s9, 0
	v_cndmask_b32_e32 v4, v2, v4, vcc
	v_lshlrev_b32_e32 v14, 2, v4
	v_xor_b32_e32 v4, 8, v2
	v_cmp_lt_i32_e32 vcc, v4, v3
	s_lshl_b64 s[10:11], s[98:99], 2
	s_lshl_b64 s[12:13], s[100:101], 2
	v_cndmask_b32_e32 v4, v2, v4, vcc
	v_lshlrev_b32_e32 v15, 2, v4
	v_xor_b32_e32 v4, 16, v2
	v_cmp_lt_i32_e32 vcc, v4, v3
	s_lshl_b64 s[20:21], s[100:101], 7
	s_lshl_b64 s[22:23], s[100:101], 14
	v_cndmask_b32_e32 v4, v2, v4, vcc
	v_lshlrev_b32_e32 v16, 2, v4
	v_xor_b32_e32 v4, 32, v2
	v_cmp_lt_i32_e32 vcc, v4, v3
	s_mov_b32 s26, 0xf000
	s_mov_b32 s27, 0xffff0000
	v_cndmask_b32_e32 v2, v2, v4, vcc
	v_lshl_add_u64 v[4:5], s[18:19], 0, v[8:9]
	v_lshlrev_b32_e32 v17, 2, v2
	v_lshl_add_u64 v[2:3], v[4:5], 0, s[0:1]
	s_mov_b64 s[0:1], 0x580000
	v_lshl_add_u64 v[4:5], v[4:5], 0, s[0:1]
	s_lshl_b64 s[0:1], s[98:99], 7
	v_lshl_add_u64 v[6:7], s[0:1], 0, v[8:9]
	s_mov_b64 s[0:1], 0x600000
	v_lshl_add_u64 v[6:7], v[6:7], 0, s[0:1]
	s_lshl_b64 s[0:1], s[98:99], 14
	v_or_b32_e32 v8, s0, v8
	v_mov_b32_e32 v9, s1
	s_lshl_b32 s15, s98, 5
	v_mov_b32_e32 v18, 0x358637bd
	s_mov_b32 s28, 0xf800000
	v_mov_b32_e32 v19, 0x260
	v_mov_b32_e32 v20, 0x480000
	v_mov_b32_e32 v21, 0x488000
	s_movk_i32 s29, 0x7fff
	s_mov_b32 s30, s98
	s_mov_b32 s34, 0
	v_mov_b32_e32 v56, v8
	v_mov_b32_e32 v57, v9
	s_mov_b32 s31, s15
	v_lshl_add_u64 v[58:59], s[18:19], 0, v[56:57]
	v_add_co_u32_e32 v58, vcc, 0x7c01000, v58
	s_nop 1
	v_addc_co_u32_e32 v59, vcc, 0, v59, vcc
	global_load_dwordx4 v[60:63], v[58:59], off offset:2048
	s_and_saveexec_b64 s[24:25], s[4:5]
	global_load_dwordx4 v[64:67], v[58:59], off offset:3072
	s_or_b64 exec, exec, s[24:25]
	s_and_b32 s8, s31, 0x1ffe0
	s_lshl_b32 s8, s8, 2
	s_and_saveexec_b64 s[24:25], s[6:7]
	global_load_dwordx4 v[68:71], v[58:59], off offset:3712
	v_lshl_add_u64 v[10:11], v[4:5], 0, s[8:9]
	global_load_dwordx4 v[72:75], v[10:11], off
	v_lshl_add_u64 v[10:11], v[2:3], 0, s[8:9]
	global_load_dwordx4 v[76:79], v[10:11], off
	s_or_b64 exec, exec, s[24:25]
	v_lshl_add_u64 v[56:57], v[56:57], 0, s[22:23]
	s_add_i32 s31, s31, s26
	v_lshl_add_u64 v[58:59], s[18:19], 0, v[56:57]
	v_add_co_u32_e32 v58, vcc, 0x7c01000, v58
	s_nop 1
	v_addc_co_u32_e32 v59, vcc, 0, v59, vcc
	global_load_dwordx4 v[80:83], v[58:59], off offset:2048
	s_and_saveexec_b64 s[24:25], s[4:5]
	global_load_dwordx4 v[84:87], v[58:59], off offset:3072
	s_or_b64 exec, exec, s[24:25]
	s_and_b32 s8, s31, 0x1ffe0
	s_lshl_b32 s8, s8, 2
	s_and_saveexec_b64 s[24:25], s[6:7]
	global_load_dwordx4 v[88:91], v[58:59], off offset:3712
	v_lshl_add_u64 v[10:11], v[4:5], 0, s[8:9]
	global_load_dwordx4 v[92:95], v[10:11], off
	v_lshl_add_u64 v[10:11], v[2:3], 0, s[8:9]
	global_load_dwordx4 v[96:99], v[10:11], off
	s_or_b64 exec, exec, s[24:25]
	v_lshl_add_u64 v[56:57], v[56:57], 0, s[22:23]
	s_add_i32 s31, s31, s26
	v_lshl_add_u64 v[58:59], s[18:19], 0, v[56:57]
	v_add_co_u32_e32 v58, vcc, 0x7c01000, v58
	s_nop 1
	v_addc_co_u32_e32 v59, vcc, 0, v59, vcc
	global_load_dwordx4 v[100:103], v[58:59], off offset:2048
	s_and_saveexec_b64 s[24:25], s[4:5]
	global_load_dwordx4 v[104:107], v[58:59], off offset:3072
	s_or_b64 exec, exec, s[24:25]
	s_and_b32 s8, s31, 0x1ffe0
	s_lshl_b32 s8, s8, 2
	s_and_saveexec_b64 s[24:25], s[6:7]
	global_load_dwordx4 v[108:111], v[58:59], off offset:3712
	v_lshl_add_u64 v[10:11], v[4:5], 0, s[8:9]
	global_load_dwordx4 v[112:115], v[10:11], off
	v_lshl_add_u64 v[10:11], v[2:3], 0, s[8:9]
	global_load_dwordx4 v[116:119], v[10:11], off
	s_or_b64 exec, exec, s[24:25]
	v_lshl_add_u64 v[56:57], v[56:57], 0, s[22:23]
	s_add_i32 s31, s31, s26
	v_lshl_add_u64 v[58:59], s[18:19], 0, v[56:57]
	v_add_co_u32_e32 v58, vcc, 0x7c01000, v58
	s_nop 1
	v_addc_co_u32_e32 v59, vcc, 0, v59, vcc
	global_load_dwordx4 v[120:123], v[58:59], off offset:2048
	s_and_saveexec_b64 s[24:25], s[4:5]
	global_load_dwordx4 v[124:127], v[58:59], off offset:3072
	s_or_b64 exec, exec, s[24:25]
	s_and_b32 s8, s31, 0x1ffe0
	s_lshl_b32 s8, s8, 2
	s_and_saveexec_b64 s[24:25], s[6:7]
	global_load_dwordx4 v[128:131], v[58:59], off offset:3712
	v_lshl_add_u64 v[10:11], v[4:5], 0, s[8:9]
	global_load_dwordx4 v[132:135], v[10:11], off
	v_lshl_add_u64 v[10:11], v[2:3], 0, s[8:9]
	global_load_dwordx4 v[136:139], v[10:11], off
	s_or_b64 exec, exec, s[24:25]
	s_cmp_lt_u32 s98, 0x200
	s_cselect_b32 s36, s22, 0
	s_cselect_b32 s37, s23, 0
	s_cselect_b32 s35, s26, 0
	v_lshl_add_u64 v[56:57], v[56:57], 0, s[36:37]
	s_add_i32 s31, s31, s35
	v_lshl_add_u64 v[58:59], s[18:19], 0, v[56:57]
	v_add_co_u32_e32 v58, vcc, 0x7c01000, v58
	s_nop 1
	v_addc_co_u32_e32 v59, vcc, 0, v59, vcc
	global_load_dwordx4 v[140:143], v[58:59], off offset:2048
	s_and_saveexec_b64 s[24:25], s[4:5]
	global_load_dwordx4 v[144:147], v[58:59], off offset:3072
	s_or_b64 exec, exec, s[24:25]
	s_and_b32 s8, s31, 0x1ffe0
	s_lshl_b32 s8, s8, 2
	s_and_saveexec_b64 s[24:25], s[6:7]
	global_load_dwordx4 v[148:151], v[58:59], off offset:3712
	v_lshl_add_u64 v[10:11], v[4:5], 0, s[8:9]
	global_load_dwordx4 v[152:155], v[10:11], off
	v_lshl_add_u64 v[10:11], v[2:3], 0, s[8:9]
	global_load_dwordx4 v[156:159], v[10:11], off
	s_or_b64 exec, exec, s[24:25]
	s_branch .LBB0_489
; __global__ void __launch_bounds__(512, 2) fwd_kernel(Args a) {
;     ...
;         for (int m = gw; m < MTOK; m += NGW) {
;             const bf16_t* pr = proj + (size_t)m * NPROJ;
;             { const u32x4 v = *(const u32x4*)(pr + PC_CQ + lane * 8); float s = 0.f;
;               s += bflo(v.x) * bflo(v.x) + bfhi(v.x) * bfhi(v.x) + bflo(v.y) * bflo(v.y) + bfhi(v.y) * bfhi(v.y) + bflo(v.z) * bflo(v.z) + bfhi(v.z) * bfhi(v.z) + bflo(v.w) * bflo(v.w) + bfhi(v.w) * bfhi(v.w);
;               s = wave_sum(s); if (lane == 0) rstd_q[m] = 1.0f / sqrtf(s * (1.0f / 512.0f) + RMS_EPS); }
;             { float s = 0.f; if (lane < 32) { const u32x4 v = *(const u32x4*)(pr + PC_CKV + lane * 8);
;               s += bflo(v.x) * bflo(v.x) + bfhi(v.x) * bfhi(v.x) + bflo(v.y) * bflo(v.y) + bfhi(v.y) * bfhi(v.y) + bflo(v.z) * bflo(v.z) + bfhi(v.z) * bfhi(v.z) + bflo(v.w) * bflo(v.w) + bfhi(v.w) * bfhi(v.w); }
;               s = wave_sum(s); if (lane == 0) rstd_kv[m] = 1.0f / sqrtf(s * (1.0f / 256.0f) + RMS_EPS); }
.LBB0_488:
	s_or_b64 exec, exec, s[0:1]
	s_add_i32 s34, s34, 1
	s_add_i32 s30, s30, s100
	s_add_u32 s10, s10, s12
	s_addc_u32 s11, s11, s13
	s_add_i32 s15, s15, s26
	v_lshl_add_u64 v[6:7], v[6:7], 0, s[20:21]
	s_cmpk_lt_i32 s30, 0x2000
	v_lshl_add_u64 v[8:9], v[8:9], 0, s[22:23]
	s_cbranch_scc0 .LBB0_497
.LBB0_489:
	v_lshl_add_u64 v[10:11], s[18:19], 0, v[8:9]
	s_waitcnt lgkmcnt(0)
	s_cmp_eq_u32 s34, 0
	s_cbranch_scc1 .Lp4_k0
	s_cmp_eq_u32 s34, 1
	s_cbranch_scc1 .Lp4_k1
	s_cmp_eq_u32 s34, 2
	s_cbranch_scc1 .Lp4_k2
	s_cmp_eq_u32 s34, 3
	s_cbranch_scc1 .Lp4_k3
.Lp4_k4:
	s_waitcnt vmcnt(0)
	v_mov_b32_e32 v22, v140
	v_mov_b32_e32 v23, v141
	v_mov_b32_e32 v24, v142
	v_mov_b32_e32 v25, v143
	v_mov_b32_e32 v40, v144
	v_mov_b32_e32 v41, v145
	v_mov_b32_e32 v42, v146
	v_mov_b32_e32 v43, v147
	v_mov_b32_e32 v44, v148
	v_mov_b32_e32 v45, v149
	v_mov_b32_e32 v46, v150
	v_mov_b32_e32 v47, v151
	v_mov_b32_e32 v48, v152
	v_mov_b32_e32 v49, v153
	v_mov_b32_e32 v50, v154
	v_mov_b32_e32 v51, v155
	v_mov_b32_e32 v52, v156
	v_mov_b32_e32 v53, v157
	v_mov_b32_e32 v54, v158
	v_mov_b32_e32 v55, v159
	s_branch .Lp4_go
.Lp4_k3:
	s_waitcnt vmcnt(5)
	v_mov_b32_e32 v22, v120
	v_mov_b32_e32 v23, v121
	v_mov_b32_e32 v24, v122
	v_mov_b32_e32 v25, v123
	v_mov_b32_e32 v40, v124
	v_mov_b32_e32 v41, v125
	v_mov_b32_e32 v42, v126
	v_mov_b32_e32 v43, v127
	v_mov_b32_e32 v44, v128
	v_mov_b32_e32 v45, v129
	v_mov_b32_e32 v46, v130
	v_mov_b32_e32 v47, v131
	v_mov_b32_e32 v48, v132
	v_mov_b32_e32 v49, v133
	v_mov_b32_e32 v50, v134
	v_mov_b32_e32 v51, v135
	v_mov_b32_e32 v52, v136
	v_mov_b32_e32 v53, v137
	v_mov_b32_e32 v54, v138
	v_mov_b32_e32 v55, v139
	s_branch .Lp4_go
.Lp4_k2:
	s_waitcnt vmcnt(10)
	v_mov_b32_e32 v22, v100
	v_mov_b32_e32 v23, v101
	v_mov_b32_e32 v24, v102
	v_mov_b32_e32 v25, v103
	v_mov_b32_e32 v40, v104
	v_mov_b32_e32 v41, v105
	v_mov_b32_e32 v42, v106
	v_mov_b32_e32 v43, v107
	v_mov_b32_e32 v44, v108
	v_mov_b32_e32 v45, v109
	v_mov_b32_e32 v46, v110
	v_mov_b32_e32 v47, v111
	v_mov_b32_e32 v48, v112
	v_mov_b32_e32 v49, v113
	v_mov_b32_e32 v50, v114
	v_mov_b32_e32 v51, v115
	v_mov_b32_e32 v52, v116
	v_mov_b32_e32 v53, v117
	v_mov_b32_e32 v54, v118
	v_mov_b32_e32 v55, v119
	s_branch .Lp4_go
.Lp4_k1:
	s_waitcnt vmcnt(15)
	v_mov_b32_e32 v22, v80
	v_mov_b32_e32 v23, v81
	v_mov_b32_e32 v24, v82
	v_mov_b32_e32 v25, v83
	v_mov_b32_e32 v40, v84
	v_mov_b32_e32 v41, v85
	v_mov_b32_e32 v42, v86
	v_mov_b32_e32 v43, v87
	v_mov_b32_e32 v44, v88
	v_mov_b32_e32 v45, v89
	v_mov_b32_e32 v46, v90
	v_mov_b32_e32 v47, v91
	v_mov_b32_e32 v48, v92
	v_mov_b32_e32 v49, v93
	v_mov_b32_e32 v50, v94
	v_mov_b32_e32 v51, v95
	v_mov_b32_e32 v52, v96
	v_mov_b32_e32 v53, v97
	v_mov_b32_e32 v54, v98
	v_mov_b32_e32 v55, v99
	s_branch .Lp4_go
.Lp4_k0:
	s_waitcnt vmcnt(20)
	v_mov_b32_e32 v22, v60
	v_mov_b32_e32 v23, v61
	v_mov_b32_e32 v24, v62
	v_mov_b32_e32 v25, v63
	v_mov_b32_e32 v40, v64
	v_mov_b32_e32 v41, v65
	v_mov_b32_e32 v42, v66
	v_mov_b32_e32 v43, v67
	v_mov_b32_e32 v44, v68
	v_mov_b32_e32 v45, v69
	v_mov_b32_e32 v46, v70
	v_mov_b32_e32 v47, v71
	v_mov_b32_e32 v48, v72
	v_mov_b32_e32 v49, v73
	v_mov_b32_e32 v50, v74
	v_mov_b32_e32 v51, v75
	v_mov_b32_e32 v52, v76
	v_mov_b32_e32 v53, v77
	v_mov_b32_e32 v54, v78
	v_mov_b32_e32 v55, v79
.Lp4_go:
	v_lshlrev_b32_e32 v26, 16, v22
	v_and_b32_e32 v22, 0xffff0000, v22
	v_mul_f32_e32 v22, v22, v22
	v_lshlrev_b32_e32 v27, 16, v23
	v_fmac_f32_e32 v22, v26, v26
	v_and_b32_e32 v23, 0xffff0000, v23
	v_fmac_f32_e32 v22, v27, v27
	v_lshlrev_b32_e32 v28, 16, v24
	v_fmac_f32_e32 v22, v23, v23
	v_and_b32_e32 v24, 0xffff0000, v24
	v_fmac_f32_e32 v22, v28, v28
	v_lshlrev_b32_e32 v29, 16, v25
	v_fmac_f32_e32 v22, v24, v24
	v_fmac_f32_e32 v22, v29, v29
	v_and_b32_e32 v23, 0xffff0000, v25
	v_fmac_f32_e32 v22, v23, v23
	ds_bpermute_b32 v23, v12, v22
	s_waitcnt lgkmcnt(0)
	v_add_f32_e32 v22, v22, v23
	ds_bpermute_b32 v23, v13, v22
	s_waitcnt lgkmcnt(0)
	v_add_f32_e32 v22, v22, v23
	ds_bpermute_b32 v23, v14, v22
	s_waitcnt lgkmcnt(0)
	v_add_f32_e32 v22, v22, v23
	ds_bpermute_b32 v23, v15, v22
	s_waitcnt lgkmcnt(0)
	v_add_f32_e32 v22, v22, v23
	ds_bpermute_b32 v23, v16, v22
	s_waitcnt lgkmcnt(0)
	v_add_f32_e32 v22, v22, v23
	ds_bpermute_b32 v23, v17, v22
	s_and_saveexec_b64 s[24:25], s[2:3]
	s_cbranch_execz .LBB0_491
	s_waitcnt lgkmcnt(0)
	v_add_f32_e32 v22, v22, v23
	v_fmamk_f32 v22, v22, 0x3b000000, v18
	v_mul_f32_e32 v23, 0x4f800000, v22
	v_cmp_gt_f32_e32 vcc, s28, v22
	s_nop 1
	v_cndmask_b32_e32 v22, v22, v23, vcc
	v_sqrt_f32_e32 v23, v22
	s_nop 0
	v_add_u32_e32 v24, -1, v23
	v_fma_f32 v26, -v24, v23, v22
	v_add_u32_e32 v25, 1, v23
	v_cmp_ge_f32_e64 s[0:1], 0, v26
	s_nop 1
	v_cndmask_b32_e64 v24, v23, v24, s[0:1]
	v_fma_f32 v23, -v25, v23, v22
	v_cmp_lt_f32_e64 s[0:1], 0, v23
	s_nop 1
	v_cndmask_b32_e64 v23, v24, v25, s[0:1]
	v_mul_f32_e32 v24, 0x37800000, v23
	v_cndmask_b32_e32 v23, v23, v24, vcc
	v_cmp_class_f32_e32 vcc, v22, v19
	s_nop 1
	v_cndmask_b32_e32 v22, v23, v22, vcc
	v_div_scale_f32 v23, s[0:1], v22, v22, 1.0
	v_rcp_f32_e32 v24, v23
	s_add_u32 s0, s18, s10
	s_addc_u32 s1, s19, s11
	v_fma_f32 v25, -v23, v24, 1.0
	v_fmac_f32_e32 v24, v25, v24
	v_div_scale_f32 v25, vcc, 1.0, v22, 1.0
	v_mul_f32_e32 v26, v25, v24
	v_fma_f32 v27, -v23, v26, v25
	v_fmac_f32_e32 v26, v27, v24
	v_fma_f32 v23, -v23, v26, v25
	v_div_fmas_f32 v23, v23, v24, v26
	v_div_fixup_f32 v22, v23, v22, 1.0
	global_store_dword v20, v22, s[0:1]
.LBB0_491:
	s_or_b64 exec, exec, s[24:25]
	v_mov_b32_e32 v22, 0
	s_and_saveexec_b64 s[0:1], s[4:5]
	s_cbranch_execz .LBB0_493
	v_add_co_u32_e32 v22, vcc, 0x7c01000, v10
	s_waitcnt lgkmcnt(0)
	s_nop 0
	v_addc_co_u32_e32 v23, vcc, 0, v11, vcc
	v_mov_b32_e32 v22, v40
	v_mov_b32_e32 v23, v41
	v_mov_b32_e32 v24, v42
	v_mov_b32_e32 v25, v43
	v_lshlrev_b32_e32 v26, 16, v22
	v_and_b32_e32 v27, 0xffff0000, v22
	v_and_b32_e32 v22, 0xffff0000, v23
	v_lshlrev_b32_e32 v23, 16, v23
	v_pk_mul_f32 v[26:27], v[26:27], v[26:27]
	v_pk_mul_f32 v[22:23], v[22:23], v[22:23]
	v_add_f32_e32 v26, v26, v27
	v_and_b32_e32 v28, 0xffff0000, v24
	v_lshlrev_b32_e32 v29, 16, v24
	v_add_f32_e32 v23, v23, v26
	v_pk_mul_f32 v[28:29], v[28:29], v[28:29]
	v_add_f32_e32 v22, v22, v23
	v_and_b32_e32 v24, 0xffff0000, v25
	v_lshlrev_b32_e32 v25, 16, v25
	v_add_f32_e32 v22, v29, v22
	v_pk_mul_f32 v[24:25], v[24:25], v[24:25]
	v_add_f32_e32 v22, v28, v22
	v_add_f32_e32 v22, v25, v22
	v_add_f32_e32 v22, v24, v22

; __device__ __forceinline__ unsigned pk2(float lo, float hi) { return f2bf(lo) | (f2bf(hi) << 16); }
; __global__ void __launch_bounds__(512, 2) fwd_kernel(Args a) {
;     ...
;             if (lane < 8) { const u32x4 v = *(const u32x4*)(pr + PC_KR + lane * 8); const int pos = m & (SEQ - 1), i0 = lane * 4;
;                 const f32x4 cs = *(const f32x4*)(cost + pos * 32 + i0), sn = *(const f32x4*)(sint + pos * 32 + i0);
;                 const f32x4 x1 = {bflo(v.x), bfhi(v.x), bflo(v.y), bfhi(v.y)}, x2 = {bflo(v.z), bfhi(v.z), bflo(v.w), bfhi(v.w)};
;                 const f32x4 o1 = x1 * cs - x2 * sn, o2 = x1 * sn + x2 * cs;
;                 u32x4 wv; wv.x = pk2(o1[0], o1[1]); wv.y = pk2(o1[2], o1[3]); wv.z = pk2(o2[0], o2[1]); wv.w = pk2(o2[2], o2[3]);
;                 *(u32x4*)(krope + (size_t)m * 64 + lane * 8) = wv; }
.LBB0_495:
	s_or_b64 exec, exec, s[24:25]
	s_and_saveexec_b64 s[0:1], s[6:7]
	s_cbranch_execz .LBB0_488
	v_add_co_u32_e32 v10, vcc, 0x7c01000, v10
	s_and_b32 s8, s15, 0x1ffe0
	s_nop 0
	v_addc_co_u32_e32 v11, vcc, 0, v11, vcc
	s_lshl_b32 s8, s8, 2
	s_waitcnt lgkmcnt(0)
	v_mov_b32_e32 v22, v44
	v_mov_b32_e32 v23, v45
	v_mov_b32_e32 v24, v46
	v_mov_b32_e32 v25, v47
	v_mov_b32_e32 v26, v48
	v_mov_b32_e32 v27, v49
	v_mov_b32_e32 v28, v50
	v_mov_b32_e32 v29, v51
	v_mov_b32_e32 v30, v52
	v_mov_b32_e32 v31, v53
	v_mov_b32_e32 v32, v54
	v_mov_b32_e32 v33, v55
	v_lshl_add_u64 v[10:11], v[4:5], 0, s[8:9]
	v_lshl_add_u64 v[10:11], v[2:3], 0, s[8:9]
	v_lshlrev_b32_e32 v34, 16, v24
	v_and_b32_e32 v35, 0xffff0000, v24
	v_lshlrev_b32_e32 v24, 16, v25
	v_and_b32_e32 v25, 0xffff0000, v25
	v_lshlrev_b32_e32 v10, 16, v22
	v_and_b32_e32 v11, 0xffff0000, v22
	v_lshlrev_b32_e32 v22, 16, v23
	v_and_b32_e32 v23, 0xffff0000, v23
	v_pk_mul_f32 v[36:37], v[26:27], v[34:35]
	v_pk_mul_f32 v[38:39], v[28:29], v[24:25]
	v_pk_mul_f32 v[34:35], v[30:31], v[34:35]
	v_pk_mul_f32 v[24:25], v[32:33], v[24:25]
	v_pk_fma_f32 v[32:33], v[32:33], v[22:23], v[38:39] neg_lo:[0,0,1] neg_hi:[0,0,1]
	v_pk_fma_f32 v[30:31], v[30:31], v[10:11], v[36:37] neg_lo:[0,0,1] neg_hi:[0,0,1]
	v_pk_fma_f32 v[22:23], v[28:29], v[22:23], v[24:25]
	v_pk_fma_f32 v[10:11], v[26:27], v[10:11], v[34:35]
	v_bfe_u32 v24, v30, 16, 1
	v_bfe_u32 v26, v32, 16, 1
	v_bfe_u32 v28, v10, 16, 1
	v_bfe_u32 v34, v22, 16, 1
	v_bfe_u32 v25, v31, 16, 1
	v_bfe_u32 v27, v33, 16, 1
	v_bfe_u32 v29, v11, 16, 1
	v_bfe_u32 v35, v23, 16, 1
	v_add3_u32 v24, v30, v24, s29
	v_add3_u32 v26, v32, v26, s29
	v_add3_u32 v10, v10, v28, s29
	v_add3_u32 v22, v22, v34, s29
	v_add3_u32 v25, v31, v25, s29
	v_add3_u32 v27, v33, v27, s29
	v_add3_u32 v11, v11, v29, s29
	v_add3_u32 v28, v23, v35, s29
	v_lshrrev_b32_e32 v23, 16, v24
	v_lshrrev_b32_e32 v24, 16, v26
	v_lshrrev_b32_e32 v10, 16, v10
	v_lshrrev_b32_e32 v26, 16, v22
	v_and_or_b32 v22, v25, s27, v23
	v_and_or_b32 v23, v27, s27, v24
	v_and_or_b32 v24, v11, s27, v10
	v_and_or_b32 v25, v28, s27, v26
	v_lshl_add_u64 v[10:11], s[18:19], 0, v[6:7]
	global_store_dwordx4 v[10:11], v[22:25], off
	s_branch .LBB0_488
